# P1 gate epilogue: -log2e folded into rstd and bias (one fma per element); P5 gelu |x| via fma source modifier; on top of v27
# baseline (speedup 1.0000x reference)
; __device__ __forceinline__ u32x4 pack8(const float* f) { u32x4 w; w.x = cvt_pk_bf16(f[0], f[1]); w.y = cvt_pk_bf16(f[2], f[3]); w.z = cvt_pk_bf16(f[4], f[5]); w.w = cvt_pk_bf16(f[6], f[7]); return w; }
;     __device__ __forceinline__ void operator()(AccT& acc, const Unit& u, int wr, int wc, int fr, int fq) const {
;     ...
;             for (int m = 0; m < 4; ++m) rsv[ai][m] = ssq[u.pm * 256 + ai * 128 + wr * 64 + m * 16 + fr];
; #pragma unroll
;         for (int ai = 0; ai < 2; ++ai)
; #pragma unroll
;             for (int m = 0; m < 4; ++m) {
;                 const int row = u.pm * 256 + ai * 128 + wr * 64 + m * 16 + fr;
;                 const float rs = __builtin_amdgcn_rsqf(rsv[ai][m] * (1.0f / 1024.0f) + EPS);
;                 bf16_t* rowp = P + (size_t)row * INW + col0;
; #pragma unroll
;                 for (int bj = 0; bj < 2; ++bj) {
;                     float v[8];
; #pragma unroll
;                     for (int n = 0; n < 2; ++n)
; #pragma unroll
;                         for (int j = 0; j < 4; ++j) {
;                             float x = acc[ai][bj][m][n][j] * rs;
;                             if (gate) { x += gb[bj][n][j]; x = __builtin_amdgcn_rcpf(1.0f + __builtin_amdgcn_exp2f(-LOG2E * x)); }
;                             v[n * 4 + j] = x;
;                         }
;                     *(u32x4*)(rowp + bj * 128) = pack8(v);
;                 }
.LBB0_185:
	s_lshl_b32 s0, s49, 8
	s_add_i32 s0, s0, s33
	v_add_u32_e32 v160, s0, v160
	v_ashrrev_i32_e32 v161, 31, v160
	v_lshl_add_u64 v[156:157], v[160:161], 2, s[46:47]
	global_load_dword v161, v[156:157], off
	global_load_dword v179, v[156:157], off offset:64
	global_load_dword v177, v[156:157], off offset:128
	global_load_dword v175, v[156:157], off offset:192
	global_load_dword v173, v[156:157], off offset:512
	global_load_dword v171, v[156:157], off offset:576
	global_load_dword v169, v[156:157], off offset:640
	global_load_dword v167, v[156:157], off offset:704
	v_add_u32_e32 v178, 16, v160
	v_add_u32_e32 v176, 32, v160
	v_add_u32_e32 v174, 48, v160
	v_add_u32_e32 v172, 0x80, v160
	v_add_u32_e32 v170, 0x90, v160
	v_add_u32_e32 v168, 0xa0, v160
	v_add_u32_e32 v166, 0xb0, v160
	v_lshlrev_b64 v[158:159], 1, v[158:159]
	s_andn2_b64 vcc, exec, s[40:41]
	s_waitcnt vmcnt(0) lgkmcnt(0)
	s_cmp_eq_u64 s[42:43], 0
	s_cbranch_scc1 .Lmy_p1_nongate
	v_mul_f32_e32 v214, 0xbfb8aa3b, v52
	v_mul_f32_e32 v215, 0xbfb8aa3b, v53
	v_mul_f32_e32 v216, 0xbfb8aa3b, v54
	v_mul_f32_e32 v217, 0xbfb8aa3b, v55
	v_mul_f32_e32 v218, 0xbfb8aa3b, v44
	v_mul_f32_e32 v219, 0xbfb8aa3b, v45
	v_mul_f32_e32 v220, 0xbfb8aa3b, v46
	v_mul_f32_e32 v221, 0xbfb8aa3b, v47
	v_mul_f32_e32 v238, 0xbfb8aa3b, v40
	v_mul_f32_e32 v239, 0xbfb8aa3b, v41
	v_mul_f32_e32 v240, 0xbfb8aa3b, v42
	v_mul_f32_e32 v241, 0xbfb8aa3b, v43
	v_mul_f32_e32 v242, 0xbfb8aa3b, v32
	v_mul_f32_e32 v243, 0xbfb8aa3b, v33
	v_mul_f32_e32 v244, 0xbfb8aa3b, v34
	v_mul_f32_e32 v245, 0xbfb8aa3b, v35
	v_fmamk_f32 v156, v161, 0x3a800000, v223
	v_rsq_f32_e32 v180, v156
	s_nop 0
	v_mul_f32_e32 v180, 0xbfb8aa3b, v180
	v_mov_b64_e32 v[156:157], s[84:85]
	v_mad_i64_i32 v[160:161], s[0:1], v160, s89, v[156:157]
	v_lshl_add_u64 v[160:161], v[160:161], 0, v[158:159]
	v_fma_f32 v206, v142, v180, v214
	v_fma_f32 v207, v143, v180, v215
	v_fma_f32 v208, v144, v180, v216
	v_fma_f32 v209, v145, v180, v217
	v_fma_f32 v210, v138, v180, v218
	v_fma_f32 v211, v139, v180, v219
	v_fma_f32 v212, v140, v180, v220
	v_fma_f32 v213, v141, v180, v221
	v_exp_f32_e32 v206, v206
	v_exp_f32_e32 v207, v207
	v_exp_f32_e32 v208, v208
	v_exp_f32_e32 v209, v209
	v_exp_f32_e32 v210, v210
	v_exp_f32_e32 v211, v211
	v_exp_f32_e32 v212, v212
	v_exp_f32_e32 v213, v213
	v_add_f32_e32 v206, 1.0, v206
	v_add_f32_e32 v207, 1.0, v207
	v_add_f32_e32 v208, 1.0, v208
	v_add_f32_e32 v209, 1.0, v209
	v_add_f32_e32 v210, 1.0, v210
	v_add_f32_e32 v211, 1.0, v211
	v_add_f32_e32 v212, 1.0, v212
	v_add_f32_e32 v213, 1.0, v213
	v_rcp_f32_e32 v142, v206
	v_rcp_f32_e32 v143, v207
	v_rcp_f32_e32 v144, v208
	v_rcp_f32_e32 v145, v209
	v_rcp_f32_e32 v181, v210
	v_rcp_f32_e32 v182, v211
	v_rcp_f32_e32 v183, v212
	v_rcp_f32_e32 v141, v213
	v_cvt_pk_bf16_f32 v138, v142, v143
	v_cvt_pk_bf16_f32 v139, v144, v145
	v_cvt_pk_bf16_f32 v140, v181, v182
	v_cvt_pk_bf16_f32 v141, v183, v141
	global_store_dwordx4 v[160:161], v[138:141], off
	s_nop 1
	v_fma_f32 v206, v134, v180, v238
	v_fma_f32 v207, v135, v180, v239
	v_fma_f32 v208, v136, v180, v240
	v_fma_f32 v209, v137, v180, v241
	v_fma_f32 v210, v130, v180, v242
	v_fma_f32 v211, v131, v180, v243
	v_fma_f32 v212, v132, v180, v244
	v_fma_f32 v213, v133, v180, v245
	v_exp_f32_e32 v206, v206
	v_exp_f32_e32 v207, v207
	v_exp_f32_e32 v208, v208
	v_exp_f32_e32 v209, v209
	v_exp_f32_e32 v210, v210
	v_exp_f32_e32 v211, v211
	v_exp_f32_e32 v212, v212
	v_exp_f32_e32 v213, v213
	v_add_f32_e32 v206, 1.0, v206
	v_add_f32_e32 v207, 1.0, v207
	v_add_f32_e32 v208, 1.0, v208
	v_add_f32_e32 v209, 1.0, v209
	v_add_f32_e32 v210, 1.0, v210
	v_add_f32_e32 v211, 1.0, v211
	v_add_f32_e32 v212, 1.0, v212
	v_add_f32_e32 v213, 1.0, v213
	v_rcp_f32_e32 v134, v206
	v_rcp_f32_e32 v135, v207
	v_rcp_f32_e32 v136, v208
	v_rcp_f32_e32 v137, v209
	v_rcp_f32_e32 v138, v210
	v_rcp_f32_e32 v139, v211
	v_rcp_f32_e32 v140, v212
	v_rcp_f32_e32 v133, v213
	v_cvt_pk_bf16_f32 v130, v134, v135
	v_cvt_pk_bf16_f32 v131, v136, v137
	v_cvt_pk_bf16_f32 v132, v138, v139
	v_cvt_pk_bf16_f32 v133, v140, v133
	global_store_dwordx4 v[160:161], v[130:133], off offset:256
	s_nop 1
	v_fmamk_f32 v130, v179, 0x3a800000, v223
	v_rsq_f32_e32 v132, v130
	s_nop 0
	v_mul_f32_e32 v132, 0xbfb8aa3b, v132
	v_mad_i64_i32 v[130:131], s[0:1], v178, s89, v[156:157]
	v_lshl_add_u64 v[130:131], v[130:131], 0, v[158:159]
	v_fma_f32 v206, v126, v132, v214
	v_fma_f32 v207, v127, v132, v215
	v_fma_f32 v208, v128, v132, v216
	v_fma_f32 v209, v129, v132, v217
	v_fma_f32 v210, v122, v132, v218
	v_fma_f32 v211, v123, v132, v219
	v_fma_f32 v212, v124, v132, v220
	v_fma_f32 v213, v125, v132, v221
	v_exp_f32_e32 v206, v206
	v_exp_f32_e32 v207, v207
	v_exp_f32_e32 v208, v208
	v_exp_f32_e32 v209, v209
	v_exp_f32_e32 v210, v210
	v_exp_f32_e32 v211, v211
	v_exp_f32_e32 v212, v212
	v_exp_f32_e32 v213, v213
	v_add_f32_e32 v206, 1.0, v206
	v_add_f32_e32 v207, 1.0, v207
	v_add_f32_e32 v208, 1.0, v208
	v_add_f32_e32 v209, 1.0, v209
	v_add_f32_e32 v210, 1.0, v210
	v_add_f32_e32 v211, 1.0, v211
	v_add_f32_e32 v212, 1.0, v212
	v_add_f32_e32 v213, 1.0, v213
	v_rcp_f32_e32 v126, v206
	v_rcp_f32_e32 v127, v207
	v_rcp_f32_e32 v128, v208
	v_rcp_f32_e32 v129, v209
	v_rcp_f32_e32 v133, v210
	v_rcp_f32_e32 v134, v211
	v_rcp_f32_e32 v135, v212
	v_rcp_f32_e32 v125, v213
	v_cvt_pk_bf16_f32 v122, v126, v127
	v_cvt_pk_bf16_f32 v123, v128, v129
	v_cvt_pk_bf16_f32 v124, v133, v134
	v_cvt_pk_bf16_f32 v125, v135, v125
	global_store_dwordx4 v[130:131], v[122:125], off
	s_nop 1
	v_fma_f32 v206, v118, v132, v238
	v_fma_f32 v207, v119, v132, v239
	v_fma_f32 v208, v120, v132, v240
	v_fma_f32 v209, v121, v132, v241
	v_fma_f32 v210, v114, v132, v242
; __device__ __forceinline__ u32x4 pack8(const float* f) { u32x4 w; w.x = cvt_pk_bf16(f[0], f[1]); w.y = cvt_pk_bf16(f[2], f[3]); w.z = cvt_pk_bf16(f[4], f[5]); w.w = cvt_pk_bf16(f[6], f[7]); return w; }
;     __device__ __forceinline__ void operator()(AccT& acc, const Unit& u, int wr, int wc, int fr, int fq) const {
;     ...
;         for (int ai = 0; ai < 2; ++ai)
; #pragma unroll
;             for (int m = 0; m < 4; ++m) {
;                 const int row = u.pm * 256 + ai * 128 + wr * 64 + m * 16 + fr;
;                 const float rs = __builtin_amdgcn_rsqf(rsv[ai][m] * (1.0f / 1024.0f) + EPS);
;                 bf16_t* rowp = P + (size_t)row * INW + col0;
; #pragma unroll
;                 for (int bj = 0; bj < 2; ++bj) {
;                     float v[8];
; #pragma unroll
;                     for (int n = 0; n < 2; ++n)
; #pragma unroll
;                         for (int j = 0; j < 4; ++j) {
;                             float x = acc[ai][bj][m][n][j] * rs;
;                             if (gate) { x += gb[bj][n][j]; x = __builtin_amdgcn_rcpf(1.0f + __builtin_amdgcn_exp2f(-LOG2E * x)); }
;                             v[n * 4 + j] = x;
;                         }
;                     *(u32x4*)(rowp + bj * 128) = pack8(v);
;                 }
	v_fma_f32 v211, v115, v132, v243
	v_fma_f32 v212, v116, v132, v244
	v_fma_f32 v213, v117, v132, v245
	v_exp_f32_e32 v206, v206
	v_exp_f32_e32 v207, v207
	v_exp_f32_e32 v208, v208
	v_exp_f32_e32 v209, v209
	v_exp_f32_e32 v210, v210
	v_exp_f32_e32 v211, v211
	v_exp_f32_e32 v212, v212
	v_exp_f32_e32 v213, v213
	v_add_f32_e32 v206, 1.0, v206
	v_add_f32_e32 v207, 1.0, v207
	v_add_f32_e32 v208, 1.0, v208
	v_add_f32_e32 v209, 1.0, v209
	v_add_f32_e32 v210, 1.0, v210
	v_add_f32_e32 v211, 1.0, v211
	v_add_f32_e32 v212, 1.0, v212
	v_add_f32_e32 v213, 1.0, v213
	v_rcp_f32_e32 v118, v206
	v_rcp_f32_e32 v119, v207
	v_rcp_f32_e32 v120, v208
	v_rcp_f32_e32 v121, v209
	v_rcp_f32_e32 v122, v210
	v_rcp_f32_e32 v123, v211
	v_rcp_f32_e32 v124, v212
	v_rcp_f32_e32 v117, v213
	v_cvt_pk_bf16_f32 v114, v118, v119
	v_cvt_pk_bf16_f32 v115, v120, v121
	v_cvt_pk_bf16_f32 v116, v122, v123
	v_cvt_pk_bf16_f32 v117, v124, v117
	global_store_dwordx4 v[130:131], v[114:117], off offset:256
	s_nop 1
	v_fmamk_f32 v114, v177, 0x3a800000, v223
	v_rsq_f32_e32 v116, v114
	s_nop 0
	v_mul_f32_e32 v116, 0xbfb8aa3b, v116
	v_mad_i64_i32 v[114:115], s[0:1], v176, s89, v[156:157]
	v_lshl_add_u64 v[114:115], v[114:115], 0, v[158:159]
	v_fma_f32 v206, v110, v116, v214
	v_fma_f32 v207, v111, v116, v215
	v_fma_f32 v208, v112, v116, v216
	v_fma_f32 v209, v113, v116, v217
	v_fma_f32 v210, v106, v116, v218
	v_fma_f32 v211, v107, v116, v219
	v_fma_f32 v212, v108, v116, v220
	v_fma_f32 v213, v109, v116, v221
	v_exp_f32_e32 v206, v206
	v_exp_f32_e32 v207, v207
	v_exp_f32_e32 v208, v208
	v_exp_f32_e32 v209, v209
	v_exp_f32_e32 v210, v210
	v_exp_f32_e32 v211, v211
	v_exp_f32_e32 v212, v212
	v_exp_f32_e32 v213, v213
	v_add_f32_e32 v206, 1.0, v206
	v_add_f32_e32 v207, 1.0, v207
	v_add_f32_e32 v208, 1.0, v208
	v_add_f32_e32 v209, 1.0, v209
	v_add_f32_e32 v210, 1.0, v210
	v_add_f32_e32 v211, 1.0, v211
	v_add_f32_e32 v212, 1.0, v212
	v_add_f32_e32 v213, 1.0, v213
	v_rcp_f32_e32 v110, v206
	v_rcp_f32_e32 v111, v207
	v_rcp_f32_e32 v112, v208
	v_rcp_f32_e32 v113, v209
	v_rcp_f32_e32 v117, v210
	v_rcp_f32_e32 v118, v211
	v_rcp_f32_e32 v119, v212
	v_rcp_f32_e32 v109, v213
	v_cvt_pk_bf16_f32 v106, v110, v111
	v_cvt_pk_bf16_f32 v107, v112, v113
	v_cvt_pk_bf16_f32 v108, v117, v118
	v_cvt_pk_bf16_f32 v109, v119, v109
	global_store_dwordx4 v[114:115], v[106:109], off
	s_nop 1
	v_fma_f32 v206, v102, v116, v238
	v_fma_f32 v207, v103, v116, v239
	v_fma_f32 v208, v104, v116, v240
	v_fma_f32 v209, v105, v116, v241
	v_fma_f32 v210, v98, v116, v242
	v_fma_f32 v211, v99, v116, v243
	v_fma_f32 v212, v100, v116, v244
	v_fma_f32 v213, v101, v116, v245
	v_exp_f32_e32 v206, v206
	v_exp_f32_e32 v207, v207
	v_exp_f32_e32 v208, v208
	v_exp_f32_e32 v209, v209
	v_exp_f32_e32 v210, v210
	v_exp_f32_e32 v211, v211
	v_exp_f32_e32 v212, v212
	v_exp_f32_e32 v213, v213
	v_add_f32_e32 v206, 1.0, v206
	v_add_f32_e32 v207, 1.0, v207
	v_add_f32_e32 v208, 1.0, v208
	v_add_f32_e32 v209, 1.0, v209
	v_add_f32_e32 v210, 1.0, v210
	v_add_f32_e32 v211, 1.0, v211
	v_add_f32_e32 v212, 1.0, v212
	v_add_f32_e32 v213, 1.0, v213
	v_rcp_f32_e32 v102, v206
	v_rcp_f32_e32 v103, v207
	v_rcp_f32_e32 v104, v208
	v_rcp_f32_e32 v105, v209
	v_rcp_f32_e32 v106, v210
	v_rcp_f32_e32 v107, v211
	v_rcp_f32_e32 v108, v212
	v_rcp_f32_e32 v101, v213
	v_cvt_pk_bf16_f32 v98, v102, v103
	v_cvt_pk_bf16_f32 v99, v104, v105
	v_cvt_pk_bf16_f32 v100, v106, v107
	v_cvt_pk_bf16_f32 v101, v108, v101
	global_store_dwordx4 v[114:115], v[98:101], off offset:256
	s_nop 1
	v_fmamk_f32 v98, v175, 0x3a800000, v223
	v_rsq_f32_e32 v100, v98
	s_nop 0
	v_mul_f32_e32 v100, 0xbfb8aa3b, v100
	v_mad_i64_i32 v[98:99], s[0:1], v174, s89, v[156:157]
	v_lshl_add_u64 v[98:99], v[98:99], 0, v[158:159]
	v_fma_f32 v206, v92, v100, v214
	v_fma_f32 v207, v93, v100, v215
	v_fma_f32 v208, v94, v100, v216
	v_fma_f32 v209, v95, v100, v217
	v_fma_f32 v210, v88, v100, v218
	v_fma_f32 v211, v89, v100, v219
	v_fma_f32 v212, v90, v100, v220
	v_fma_f32 v213, v91, v100, v221
	v_exp_f32_e32 v206, v206
	v_exp_f32_e32 v207, v207
	v_exp_f32_e32 v208, v208
	v_exp_f32_e32 v209, v209
	v_exp_f32_e32 v210, v210
	v_exp_f32_e32 v211, v211
	v_exp_f32_e32 v212, v212
	v_exp_f32_e32 v213, v213
	v_add_f32_e32 v206, 1.0, v206
	v_add_f32_e32 v207, 1.0, v207
	v_add_f32_e32 v208, 1.0, v208
	v_add_f32_e32 v209, 1.0, v209
	v_add_f32_e32 v210, 1.0, v210
	v_add_f32_e32 v211, 1.0, v211
	v_add_f32_e32 v212, 1.0, v212
	v_add_f32_e32 v213, 1.0, v213
	v_rcp_f32_e32 v92, v206
	v_rcp_f32_e32 v93, v207
	v_rcp_f32_e32 v94, v208
	v_rcp_f32_e32 v95, v209
	v_rcp_f32_e32 v101, v210
	v_rcp_f32_e32 v102, v211
	v_rcp_f32_e32 v103, v212
	v_rcp_f32_e32 v91, v213
	v_cvt_pk_bf16_f32 v88, v92, v93
	v_cvt_pk_bf16_f32 v89, v94, v95
	v_cvt_pk_bf16_f32 v90, v101, v102
	v_cvt_pk_bf16_f32 v91, v103, v91
	global_store_dwordx4 v[98:99], v[88:91], off
	s_nop 1
	v_fma_f32 v206, v84, v100, v238
	v_fma_f32 v207, v85, v100, v239
	v_fma_f32 v208, v86, v100, v240
	v_fma_f32 v209, v87, v100, v241
	v_fma_f32 v210, v80, v100, v242
	v_fma_f32 v211, v81, v100, v243
	v_fma_f32 v212, v82, v100, v244
	v_fma_f32 v213, v83, v100, v245
	v_exp_f32_e32 v206, v206
	v_exp_f32_e32 v207, v207
	v_exp_f32_e32 v208, v208
	v_exp_f32_e32 v209, v209
	v_exp_f32_e32 v210, v210
	v_exp_f32_e32 v211, v211
	v_exp_f32_e32 v212, v212
	v_exp_f32_e32 v213, v213
	v_add_f32_e32 v206, 1.0, v206
	v_add_f32_e32 v207, 1.0, v207
	v_add_f32_e32 v208, 1.0, v208
	v_add_f32_e32 v209, 1.0, v209
	v_add_f32_e32 v210, 1.0, v210
	v_add_f32_e32 v211, 1.0, v211
	v_add_f32_e32 v212, 1.0, v212
	v_add_f32_e32 v213, 1.0, v213
	v_rcp_f32_e32 v84, v206
	v_rcp_f32_e32 v85, v207
	v_rcp_f32_e32 v86, v208
	v_rcp_f32_e32 v87, v209
; __device__ __forceinline__ u32x4 pack8(const float* f) { u32x4 w; w.x = cvt_pk_bf16(f[0], f[1]); w.y = cvt_pk_bf16(f[2], f[3]); w.z = cvt_pk_bf16(f[4], f[5]); w.w = cvt_pk_bf16(f[6], f[7]); return w; }
;     __device__ __forceinline__ void operator()(AccT& acc, const Unit& u, int wr, int wc, int fr, int fq) const {
;     ...
;         for (int ai = 0; ai < 2; ++ai)
; #pragma unroll
;             for (int m = 0; m < 4; ++m) {
;                 const int row = u.pm * 256 + ai * 128 + wr * 64 + m * 16 + fr;
;                 const float rs = __builtin_amdgcn_rsqf(rsv[ai][m] * (1.0f / 1024.0f) + EPS);
;                 bf16_t* rowp = P + (size_t)row * INW + col0;
; #pragma unroll
;                 for (int bj = 0; bj < 2; ++bj) {
;                     float v[8];
; #pragma unroll
;                     for (int n = 0; n < 2; ++n)
; #pragma unroll
;                         for (int j = 0; j < 4; ++j) {
;                             float x = acc[ai][bj][m][n][j] * rs;
;                             if (gate) { x += gb[bj][n][j]; x = __builtin_amdgcn_rcpf(1.0f + __builtin_amdgcn_exp2f(-LOG2E * x)); }
;                             v[n * 4 + j] = x;
;                         }
;                     *(u32x4*)(rowp + bj * 128) = pack8(v);
;                 }
	v_rcp_f32_e32 v88, v210
	v_rcp_f32_e32 v89, v211
	v_rcp_f32_e32 v90, v212
	v_rcp_f32_e32 v83, v213
	v_cvt_pk_bf16_f32 v80, v84, v85
	v_cvt_pk_bf16_f32 v81, v86, v87
	v_cvt_pk_bf16_f32 v82, v88, v89
	v_cvt_pk_bf16_f32 v83, v90, v83
	global_store_dwordx4 v[98:99], v[80:83], off offset:256
	s_nop 1
	v_fmamk_f32 v80, v173, 0x3a800000, v223
	v_rsq_f32_e32 v82, v80
	s_nop 0
	v_mul_f32_e32 v82, 0xbfb8aa3b, v82
	v_mad_i64_i32 v[80:81], s[0:1], v172, s89, v[156:157]
	v_lshl_add_u64 v[80:81], v[80:81], 0, v[158:159]
	v_fma_f32 v206, v76, v82, v214
	v_fma_f32 v207, v77, v82, v215
	v_fma_f32 v208, v78, v82, v216
	v_fma_f32 v209, v79, v82, v217
	v_fma_f32 v210, v72, v82, v218
	v_fma_f32 v211, v73, v82, v219
	v_fma_f32 v212, v74, v82, v220
	v_fma_f32 v213, v75, v82, v221
	v_exp_f32_e32 v206, v206
	v_exp_f32_e32 v207, v207
	v_exp_f32_e32 v208, v208
	v_exp_f32_e32 v209, v209
	v_exp_f32_e32 v210, v210
	v_exp_f32_e32 v211, v211
	v_exp_f32_e32 v212, v212
	v_exp_f32_e32 v213, v213
	v_add_f32_e32 v206, 1.0, v206
	v_add_f32_e32 v207, 1.0, v207
	v_add_f32_e32 v208, 1.0, v208
	v_add_f32_e32 v209, 1.0, v209
	v_add_f32_e32 v210, 1.0, v210
	v_add_f32_e32 v211, 1.0, v211
	v_add_f32_e32 v212, 1.0, v212
	v_add_f32_e32 v213, 1.0, v213
	v_rcp_f32_e32 v76, v206
	v_rcp_f32_e32 v77, v207
	v_rcp_f32_e32 v78, v208
	v_rcp_f32_e32 v79, v209
	v_rcp_f32_e32 v83, v210
	v_rcp_f32_e32 v84, v211
	v_rcp_f32_e32 v85, v212
	v_rcp_f32_e32 v75, v213
	v_cvt_pk_bf16_f32 v72, v76, v77
	v_cvt_pk_bf16_f32 v73, v78, v79
	v_cvt_pk_bf16_f32 v74, v83, v84
	v_cvt_pk_bf16_f32 v75, v85, v75
	global_store_dwordx4 v[80:81], v[72:75], off
	s_nop 1
	v_fma_f32 v206, v68, v82, v238
	v_fma_f32 v207, v69, v82, v239
	v_fma_f32 v208, v70, v82, v240
	v_fma_f32 v209, v71, v82, v241
	v_fma_f32 v210, v64, v82, v242
	v_fma_f32 v211, v65, v82, v243
	v_fma_f32 v212, v66, v82, v244
	v_fma_f32 v213, v67, v82, v245
	v_exp_f32_e32 v206, v206
	v_exp_f32_e32 v207, v207
	v_exp_f32_e32 v208, v208
	v_exp_f32_e32 v209, v209
	v_exp_f32_e32 v210, v210
	v_exp_f32_e32 v211, v211
	v_exp_f32_e32 v212, v212
	v_exp_f32_e32 v213, v213
	v_add_f32_e32 v206, 1.0, v206
	v_add_f32_e32 v207, 1.0, v207
	v_add_f32_e32 v208, 1.0, v208
	v_add_f32_e32 v209, 1.0, v209
	v_add_f32_e32 v210, 1.0, v210
	v_add_f32_e32 v211, 1.0, v211
	v_add_f32_e32 v212, 1.0, v212
	v_add_f32_e32 v213, 1.0, v213
	v_rcp_f32_e32 v68, v206
	v_rcp_f32_e32 v69, v207
	v_rcp_f32_e32 v70, v208
	v_rcp_f32_e32 v71, v209
	v_rcp_f32_e32 v72, v210
	v_rcp_f32_e32 v73, v211
	v_rcp_f32_e32 v74, v212
	v_rcp_f32_e32 v67, v213
	v_cvt_pk_bf16_f32 v64, v68, v69
	v_cvt_pk_bf16_f32 v65, v70, v71
	v_cvt_pk_bf16_f32 v66, v72, v73
	v_cvt_pk_bf16_f32 v67, v74, v67
	global_store_dwordx4 v[80:81], v[64:67], off offset:256
	s_nop 1
	v_fmamk_f32 v64, v171, 0x3a800000, v223
	v_rsq_f32_e32 v66, v64
	s_nop 0
	v_mul_f32_e32 v66, 0xbfb8aa3b, v66
	v_mad_i64_i32 v[64:65], s[0:1], v170, s89, v[156:157]
	v_lshl_add_u64 v[64:65], v[64:65], 0, v[158:159]
	v_fma_f32 v206, v60, v66, v214
	v_fma_f32 v207, v61, v66, v215
	v_fma_f32 v208, v62, v66, v216
	v_fma_f32 v209, v63, v66, v217
	v_fma_f32 v210, v56, v66, v218
	v_fma_f32 v211, v57, v66, v219
	v_fma_f32 v212, v58, v66, v220
	v_fma_f32 v213, v59, v66, v221
	v_exp_f32_e32 v206, v206
	v_exp_f32_e32 v207, v207
	v_exp_f32_e32 v208, v208
	v_exp_f32_e32 v209, v209
	v_exp_f32_e32 v210, v210
	v_exp_f32_e32 v211, v211
	v_exp_f32_e32 v212, v212
	v_exp_f32_e32 v213, v213
	v_add_f32_e32 v206, 1.0, v206
	v_add_f32_e32 v207, 1.0, v207
	v_add_f32_e32 v208, 1.0, v208
	v_add_f32_e32 v209, 1.0, v209
	v_add_f32_e32 v210, 1.0, v210
	v_add_f32_e32 v211, 1.0, v211
	v_add_f32_e32 v212, 1.0, v212
	v_add_f32_e32 v213, 1.0, v213
	v_rcp_f32_e32 v60, v206
	v_rcp_f32_e32 v61, v207
	v_rcp_f32_e32 v62, v208
	v_rcp_f32_e32 v63, v209
	v_rcp_f32_e32 v67, v210
	v_rcp_f32_e32 v68, v211
	v_rcp_f32_e32 v69, v212
	v_rcp_f32_e32 v59, v213
	v_cvt_pk_bf16_f32 v56, v60, v61
	v_cvt_pk_bf16_f32 v57, v62, v63
	v_cvt_pk_bf16_f32 v58, v67, v68
	v_cvt_pk_bf16_f32 v59, v69, v59
	global_store_dwordx4 v[64:65], v[56:59], off
	s_nop 1
	v_fma_f32 v206, v48, v66, v238
	v_fma_f32 v207, v49, v66, v239
	v_fma_f32 v208, v50, v66, v240
	v_fma_f32 v209, v51, v66, v241
	v_fma_f32 v210, v36, v66, v242
	v_fma_f32 v211, v37, v66, v243
	v_fma_f32 v212, v38, v66, v244
	v_fma_f32 v213, v39, v66, v245
	v_exp_f32_e32 v206, v206
	v_exp_f32_e32 v207, v207
	v_exp_f32_e32 v208, v208
	v_exp_f32_e32 v209, v209
	v_exp_f32_e32 v210, v210
	v_exp_f32_e32 v211, v211
	v_exp_f32_e32 v212, v212
	v_exp_f32_e32 v213, v213
	v_add_f32_e32 v206, 1.0, v206
	v_add_f32_e32 v207, 1.0, v207
	v_add_f32_e32 v208, 1.0, v208
	v_add_f32_e32 v209, 1.0, v209
	v_add_f32_e32 v210, 1.0, v210
	v_add_f32_e32 v211, 1.0, v211
	v_add_f32_e32 v212, 1.0, v212
	v_add_f32_e32 v213, 1.0, v213
	v_rcp_f32_e32 v48, v206
	v_rcp_f32_e32 v49, v207
	v_rcp_f32_e32 v50, v208
	v_rcp_f32_e32 v51, v209
	v_rcp_f32_e32 v56, v210
	v_rcp_f32_e32 v57, v211
	v_rcp_f32_e32 v58, v212
	v_rcp_f32_e32 v39, v213
	v_cvt_pk_bf16_f32 v36, v48, v49
	v_cvt_pk_bf16_f32 v37, v50, v51
	v_cvt_pk_bf16_f32 v38, v56, v57
	v_cvt_pk_bf16_f32 v39, v58, v39
	global_store_dwordx4 v[64:65], v[36:39], off offset:256
	s_nop 1
	v_fmamk_f32 v36, v169, 0x3a800000, v223
	v_rsq_f32_e32 v38, v36
	s_nop 0
	v_mul_f32_e32 v38, 0xbfb8aa3b, v38
	v_mad_i64_i32 v[36:37], s[0:1], v168, s89, v[156:157]
	v_lshl_add_u64 v[36:37], v[36:37], 0, v[158:159]
	v_fma_f32 v206, v28, v38, v214
	v_fma_f32 v207, v29, v38, v215
	v_fma_f32 v208, v30, v38, v216
	v_fma_f32 v209, v31, v38, v217
	v_fma_f32 v210, v24, v38, v218
	v_fma_f32 v211, v25, v38, v219
	v_fma_f32 v212, v26, v38, v220
	v_fma_f32 v213, v27, v38, v221
	v_exp_f32_e32 v206, v206
; __device__ __forceinline__ u32x4 pack8(const float* f) { u32x4 w; w.x = cvt_pk_bf16(f[0], f[1]); w.y = cvt_pk_bf16(f[2], f[3]); w.z = cvt_pk_bf16(f[4], f[5]); w.w = cvt_pk_bf16(f[6], f[7]); return w; }
;     __device__ __forceinline__ void operator()(AccT& acc, const Unit& u, int wr, int wc, int fr, int fq) const {
;     ...
;         for (int ai = 0; ai < 2; ++ai)
; #pragma unroll
;             for (int m = 0; m < 4; ++m) {
;                 const int row = u.pm * 256 + ai * 128 + wr * 64 + m * 16 + fr;
;                 const float rs = __builtin_amdgcn_rsqf(rsv[ai][m] * (1.0f / 1024.0f) + EPS);
;                 bf16_t* rowp = P + (size_t)row * INW + col0;
; #pragma unroll
;                 for (int bj = 0; bj < 2; ++bj) {
;                     float v[8];
; #pragma unroll
;                     for (int n = 0; n < 2; ++n)
; #pragma unroll
;                         for (int j = 0; j < 4; ++j) {
;                             float x = acc[ai][bj][m][n][j] * rs;
;                             if (gate) { x += gb[bj][n][j]; x = __builtin_amdgcn_rcpf(1.0f + __builtin_amdgcn_exp2f(-LOG2E * x)); }
;                             v[n * 4 + j] = x;
;                         }
;                     *(u32x4*)(rowp + bj * 128) = pack8(v);
;                 }
	v_exp_f32_e32 v207, v207
	v_exp_f32_e32 v208, v208
	v_exp_f32_e32 v209, v209
	v_exp_f32_e32 v210, v210
	v_exp_f32_e32 v211, v211
	v_exp_f32_e32 v212, v212
	v_exp_f32_e32 v213, v213
	v_add_f32_e32 v206, 1.0, v206
	v_add_f32_e32 v207, 1.0, v207
	v_add_f32_e32 v208, 1.0, v208
	v_add_f32_e32 v209, 1.0, v209
	v_add_f32_e32 v210, 1.0, v210
	v_add_f32_e32 v211, 1.0, v211
	v_add_f32_e32 v212, 1.0, v212
	v_add_f32_e32 v213, 1.0, v213
	v_rcp_f32_e32 v28, v206
	v_rcp_f32_e32 v29, v207
	v_rcp_f32_e32 v30, v208
	v_rcp_f32_e32 v31, v209
	v_rcp_f32_e32 v39, v210
	v_rcp_f32_e32 v48, v211
	v_rcp_f32_e32 v49, v212
	v_rcp_f32_e32 v27, v213
	v_cvt_pk_bf16_f32 v24, v28, v29
	v_cvt_pk_bf16_f32 v25, v30, v31
	v_cvt_pk_bf16_f32 v26, v39, v48
	v_cvt_pk_bf16_f32 v27, v49, v27
	global_store_dwordx4 v[36:37], v[24:27], off
	s_nop 1
	v_fma_f32 v206, v20, v38, v238
	v_fma_f32 v207, v21, v38, v239
	v_fma_f32 v208, v22, v38, v240
	v_fma_f32 v209, v23, v38, v241
	v_fma_f32 v210, v16, v38, v242
	v_fma_f32 v211, v17, v38, v243
	v_fma_f32 v212, v18, v38, v244
	v_fma_f32 v213, v19, v38, v245
	v_exp_f32_e32 v206, v206
	v_exp_f32_e32 v207, v207
	v_exp_f32_e32 v208, v208
	v_exp_f32_e32 v209, v209
	v_exp_f32_e32 v210, v210
	v_exp_f32_e32 v211, v211
	v_exp_f32_e32 v212, v212
	v_exp_f32_e32 v213, v213
	v_add_f32_e32 v206, 1.0, v206
	v_add_f32_e32 v207, 1.0, v207
	v_add_f32_e32 v208, 1.0, v208
	v_add_f32_e32 v209, 1.0, v209
	v_add_f32_e32 v210, 1.0, v210
	v_add_f32_e32 v211, 1.0, v211
	v_add_f32_e32 v212, 1.0, v212
	v_add_f32_e32 v213, 1.0, v213
	v_rcp_f32_e32 v20, v206
	v_rcp_f32_e32 v21, v207
	v_rcp_f32_e32 v22, v208
	v_rcp_f32_e32 v23, v209
	v_rcp_f32_e32 v24, v210
	v_rcp_f32_e32 v25, v211
	v_rcp_f32_e32 v26, v212
	v_rcp_f32_e32 v19, v213
	v_cvt_pk_bf16_f32 v16, v20, v21
	v_cvt_pk_bf16_f32 v17, v22, v23
	v_cvt_pk_bf16_f32 v18, v24, v25
	v_cvt_pk_bf16_f32 v19, v26, v19
	global_store_dwordx4 v[36:37], v[16:19], off offset:256
	s_nop 1
	v_fmamk_f32 v16, v167, 0x3a800000, v223
	v_rsq_f32_e32 v18, v16
	v_mad_i64_i32 v[16:17], s[0:1], v166, s89, v[156:157]
	v_lshl_add_u64 v[16:17], v[16:17], 0, v[158:159]
	v_fmac_f32_e32 v52, v12, v18
	v_mul_f32_e32 v19, v12, v18
	v_mul_f32_e32 v12, 0xbfb8aa3b, v52
	v_exp_f32_e32 v12, v12
	v_fmac_f32_e32 v53, v13, v18
	v_fmac_f32_e32 v54, v14, v18
	v_fmac_f32_e32 v55, v15, v18
	v_add_f32_e32 v12, 1.0, v12
	v_rcp_f32_e32 v12, v12
	v_fmac_f32_e32 v44, v8, v18
	v_fmac_f32_e32 v45, v9, v18
	v_fmac_f32_e32 v46, v10, v18
	v_cndmask_b32_e64 v12, v19, v12, s[42:43]
	v_mul_f32_e32 v19, v13, v18
	v_mul_f32_e32 v13, 0xbfb8aa3b, v53
	v_exp_f32_e32 v13, v13
	v_fmac_f32_e32 v47, v11, v18
	v_fmac_f32_e32 v40, v4, v18
	v_fmac_f32_e32 v41, v5, v18
	v_add_f32_e32 v13, 1.0, v13
	v_rcp_f32_e32 v13, v13
	v_fmac_f32_e32 v42, v6, v18
	v_fmac_f32_e32 v43, v7, v18
	v_fmac_f32_e32 v32, v0, v18
	v_cndmask_b32_e64 v13, v19, v13, s[42:43]
	v_mul_f32_e32 v19, v14, v18
	v_mul_f32_e32 v14, 0xbfb8aa3b, v54
	v_exp_f32_e32 v14, v14
	v_fmac_f32_e32 v33, v1, v18
	v_fmac_f32_e32 v34, v2, v18
	v_fmac_f32_e32 v35, v3, v18
	v_add_f32_e32 v14, 1.0, v14
	v_rcp_f32_e32 v14, v14
	s_mov_b64 s[0:1], -1
	v_cndmask_b32_e64 v14, v19, v14, s[42:43]
	v_mul_f32_e32 v19, v15, v18
	v_mul_f32_e32 v15, 0xbfb8aa3b, v55
	v_exp_f32_e32 v15, v15
	s_nop 0
	v_add_f32_e32 v15, 1.0, v15
	v_rcp_f32_e32 v15, v15
	s_nop 0
	v_cndmask_b32_e64 v15, v19, v15, s[42:43]
	v_mul_f32_e32 v19, v8, v18
	v_mul_f32_e32 v8, 0xbfb8aa3b, v44
	v_exp_f32_e32 v8, v8
	s_nop 0
	v_add_f32_e32 v8, 1.0, v8
	v_rcp_f32_e32 v8, v8
	s_nop 0
	v_cndmask_b32_e64 v19, v19, v8, s[42:43]
	v_mul_f32_e32 v8, v9, v18
	v_mul_f32_e32 v9, 0xbfb8aa3b, v45
	v_exp_f32_e32 v9, v9
	s_nop 0
	v_add_f32_e32 v9, 1.0, v9
	v_rcp_f32_e32 v9, v9
	s_nop 0
	v_cndmask_b32_e64 v20, v8, v9, s[42:43]
	v_mul_f32_e32 v9, 0xbfb8aa3b, v46
	v_exp_f32_e32 v9, v9
	v_mul_f32_e32 v8, v10, v18
	v_add_f32_e32 v9, 1.0, v9
	v_rcp_f32_e32 v9, v9
	s_nop 0
	v_cndmask_b32_e64 v21, v8, v9, s[42:43]
	v_mul_f32_e32 v9, 0xbfb8aa3b, v47
	v_exp_f32_e32 v9, v9
	v_mul_f32_e32 v8, v11, v18
	v_add_f32_e32 v9, 1.0, v9
	v_rcp_f32_e32 v9, v9
	s_nop 0
	v_cndmask_b32_e64 v11, v8, v9, s[42:43]
	v_cvt_pk_bf16_f32 v8, v12, v13
	v_cvt_pk_bf16_f32 v9, v14, v15
	v_cvt_pk_bf16_f32 v10, v19, v20
	v_cvt_pk_bf16_f32 v11, v21, v11
	global_store_dwordx4 v[16:17], v[8:11], off
	s_nop 1
	v_mul_f32_e32 v8, v4, v18
	v_mul_f32_e32 v4, 0xbfb8aa3b, v40
	v_exp_f32_e32 v4, v4
	s_nop 0
	v_add_f32_e32 v4, 1.0, v4
	v_rcp_f32_e32 v4, v4
	s_nop 0
	v_cndmask_b32_e64 v4, v8, v4, s[42:43]
	v_mul_f32_e32 v8, v5, v18
	v_mul_f32_e32 v5, 0xbfb8aa3b, v41
	v_exp_f32_e32 v5, v5
	s_nop 0
	v_add_f32_e32 v5, 1.0, v5
	v_rcp_f32_e32 v5, v5
	s_nop 0
	v_cndmask_b32_e64 v5, v8, v5, s[42:43]
	v_mul_f32_e32 v8, v6, v18
	v_mul_f32_e32 v6, 0xbfb8aa3b, v42
	v_exp_f32_e32 v6, v6
	s_nop 0
	v_add_f32_e32 v6, 1.0, v6
	v_rcp_f32_e32 v6, v6
	s_nop 0
	v_cndmask_b32_e64 v6, v8, v6, s[42:43]
	v_mul_f32_e32 v8, v7, v18
	v_mul_f32_e32 v7, 0xbfb8aa3b, v43
	v_exp_f32_e32 v7, v7
	s_nop 0
	v_add_f32_e32 v7, 1.0, v7
	v_rcp_f32_e32 v7, v7
	s_nop 0
	v_cndmask_b32_e64 v7, v8, v7, s[42:43]
	v_mul_f32_e32 v8, v0, v18
	v_mul_f32_e32 v0, 0xbfb8aa3b, v32
	v_exp_f32_e32 v0, v0
	s_nop 0
	v_add_f32_e32 v0, 1.0, v0
	v_rcp_f32_e32 v0, v0
	s_nop 0
	v_cndmask_b32_e64 v8, v8, v0, s[42:43]
	v_mul_f32_e32 v0, v1, v18
	v_mul_f32_e32 v1, 0xbfb8aa3b, v33
	v_exp_f32_e32 v1, v1
	s_nop 0
	v_add_f32_e32 v1, 1.0, v1
	v_rcp_f32_e32 v1, v1
	s_nop 0
	v_cndmask_b32_e64 v9, v0, v1, s[42:43]
	v_mul_f32_e32 v1, 0xbfb8aa3b, v34
	v_exp_f32_e32 v1, v1
	v_mul_f32_e32 v0, v2, v18
	v_add_f32_e32 v1, 1.0, v1
	v_rcp_f32_e32 v1, v1
	s_nop 0
	v_cndmask_b32_e64 v10, v0, v1, s[42:43]
	v_mul_f32_e32 v1, 0xbfb8aa3b, v35
	v_exp_f32_e32 v1, v1
	v_mul_f32_e32 v0, v3, v18
	v_add_f32_e32 v1, 1.0, v1
	v_rcp_f32_e32 v1, v1
	s_nop 0
	v_cndmask_b32_e64 v3, v0, v1, s[42:43]
	v_cvt_pk_bf16_f32 v0, v4, v5
	v_cvt_pk_bf16_f32 v1, v6, v7
	v_cvt_pk_bf16_f32 v2, v8, v9
	v_cvt_pk_bf16_f32 v3, v10, v3
	global_store_dwordx4 v[16:17], v[0:3], off offset:256
	s_branch .Lmy_p1_join

; __device__ __forceinline__ unsigned cvt_pk_bf16(float lo, float hi) { unsigned r; asm volatile("v_cvt_pk_bf16_f32 %0, %1, %2" : "=v"(r) : "v"(lo), "v"(hi)); return r; }
; __device__ __forceinline__ float ror1(float x) { return __builtin_bit_cast(float, __builtin_amdgcn_update_dpp(0, __builtin_bit_cast(int, x), 0x121, 0xf, 0xf, false)); }
; __device__ __forceinline__ f32x2 gelu_pk(f32x2 v) {
;     const f32x2 av = __builtin_elementwise_abs(v), d = av * 0.2316418882f + 1.0f;
;     f32x2 t; t.x = __builtin_amdgcn_rcpf(d.x); t.y = __builtin_amdgcn_rcpf(d.y);
;     f32x2 q = t * 0.5307027145f + (-0.7265760135f); q = q * t + 0.7107068705f; q = q * t + (-0.142248368f); q = q * t + 0.127414796f; q = q * t;
;     const f32x2 s = (v * v) * (-0.72134752044f);
;     f32x2 e; e.x = __builtin_amdgcn_exp2f(s.x); e.y = __builtin_amdgcn_exp2f(s.y);
;     const f32x2 m = v * (q * e), r = v - m;
;     f32x2 o; o.x = v.x < 0.f ? m.x : r.x; o.y = v.y < 0.f ? m.y : r.y; return o;
; }
;     __device__ __forceinline__ void operator()(AccT& acc, const Unit& u, int wr, int wc, int fr, int fq) const {
;     ...
;                     const f32x4 cg_ = acc[ai][0][m][n], cv_ = acc[ai][1][m][n];
;                     f32x4 p1g, p2g, p1v, p2v;
; #pragma unroll
;                     for (int j = 0; j < 4; ++j) {
;                         p1g[j] = ror1(fr == 15 ? hg[j] : cg_[j]); p2g[j] = ror2(fr >= 14 ? hg[j] : cg_[j]);
;                         p1v[j] = ror1(fr == 15 ? hv[j] : cv_[j]); p2v[j] = ror2(fr >= 14 ? hv[j] : cv_[j]);
;                     }
;                     const f32x4 hcg = bg + w0g * p2g + w1g * p1g + w2g * cg_;
;                     const f32x4 hcv = bv + w0v * p2v + w1v * p1v + w2v * cv_;
;                     const f32x2 ga = gelu_pk((f32x2){hcg[0], hcg[1]}), gb2 = gelu_pk((f32x2){hcg[2], hcg[3]});
;                     u32x2 w; w.x = cvt_pk_bf16(ga.x * hcv[0], ga.y * hcv[1]); w.y = cvt_pk_bf16(gb2.x * hcv[2], gb2.y * hcv[3]);
;                     const int t = tstart + rl;
;                     if (n == 0) stash[ai][m] = w;
;                     else if (rl >= 2) *(u32x4*)(U + (size_t)(arow0 + rl) * FF + colg0) = (u32x4){stash[ai][m].x, stash[ai][m].y, w.x, w.y};
;                     if (rl < 2 || rl >= 254) { float* hp = halo + ((size_t)u.pm * 4 + (rl < 2 ? rl : rl - 252)) * FF2; *(f32x4*)(hp + colg) = cg_; *(f32x4*)(hp + colv) = cv_; }
.Lmy_p5_1:
	s_or_b64 exec, exec, s[20:21]
	s_waitcnt lgkmcnt(0)
	s_nop 4
	v_mov_b32_dpp v214, v152 row_ror:1 row_mask:0xf bank_mask:0xf
	v_mov_b32_dpp v215, v153 row_ror:1 row_mask:0xf bank_mask:0xf
	v_mov_b32_dpp v216, v154 row_ror:1 row_mask:0xf bank_mask:0xf
	v_mov_b32_dpp v217, v155 row_ror:1 row_mask:0xf bank_mask:0xf
	s_nop 1
	v_cndmask_b32_e64 v164, v214, v164, s[48:49]
	v_cndmask_b32_e64 v165, v215, v165, s[48:49]
	v_cndmask_b32_e64 v166, v216, v166, s[48:49]
	v_cndmask_b32_e64 v167, v217, v167, s[48:49]
	v_mov_b32_dpp v214, v148 row_ror:1 row_mask:0xf bank_mask:0xf
	v_mov_b32_dpp v215, v149 row_ror:1 row_mask:0xf bank_mask:0xf
	v_mov_b32_dpp v216, v150 row_ror:1 row_mask:0xf bank_mask:0xf
	v_mov_b32_dpp v217, v151 row_ror:1 row_mask:0xf bank_mask:0xf
	s_nop 1
	v_cndmask_b32_e64 v168, v214, v168, s[48:49]
	v_cndmask_b32_e64 v169, v215, v169, s[48:49]
	v_cndmask_b32_e64 v170, v216, v170, s[48:49]
	v_cndmask_b32_e64 v171, v217, v171, s[48:49]
	v_mov_b32_dpp v214, v140 row_ror:1 row_mask:0xf bank_mask:0xf
	v_mov_b32_dpp v215, v141 row_ror:1 row_mask:0xf bank_mask:0xf
	v_mov_b32_dpp v216, v142 row_ror:1 row_mask:0xf bank_mask:0xf
	v_mov_b32_dpp v217, v143 row_ror:1 row_mask:0xf bank_mask:0xf
	s_nop 1
	v_cndmask_b32_e64 v234, v214, v234, s[48:49]
	v_cndmask_b32_e64 v235, v215, v235, s[48:49]
	v_cndmask_b32_e64 v236, v216, v236, s[48:49]
	v_cndmask_b32_e64 v237, v217, v237, s[48:49]
	v_mov_b32_dpp v214, v114 row_ror:1 row_mask:0xf bank_mask:0xf
	v_mov_b32_dpp v215, v115 row_ror:1 row_mask:0xf bank_mask:0xf
	v_mov_b32_dpp v216, v116 row_ror:1 row_mask:0xf bank_mask:0xf
	v_mov_b32_dpp v217, v117 row_ror:1 row_mask:0xf bank_mask:0xf
	s_nop 1
	v_cndmask_b32_e64 v250, v214, v250, s[48:49]
	v_cndmask_b32_e64 v251, v215, v251, s[48:49]
	v_cndmask_b32_e64 v252, v216, v252, s[48:49]
	v_cndmask_b32_e64 v253, v217, v253, s[48:49]
	v_pk_fma_f32 v[206:207], v[102:103], v[234:235], v[98:99]
	v_pk_fma_f32 v[210:211], v[92:93], v[250:251], v[84:85]
	v_pk_fma_f32 v[208:209], v[104:105], v[236:237], v[100:101]
	v_pk_fma_f32 v[212:213], v[94:95], v[252:253], v[86:87]
	v_pk_fma_f32 v[206:207], v[106:107], v[164:165], v[206:207]
	v_pk_fma_f32 v[210:211], v[88:89], v[168:169], v[210:211]
	v_pk_fma_f32 v[208:209], v[108:109], v[166:167], v[208:209]
	v_pk_fma_f32 v[212:213], v[90:91], v[170:171], v[212:213]
	v_pk_fma_f32 v[206:207], v[110:111], v[160:161], v[206:207]
	v_pk_fma_f32 v[210:211], v[80:81], v[156:157], v[210:211]
	v_pk_fma_f32 v[208:209], v[112:113], v[162:163], v[208:209]
	v_pk_fma_f32 v[212:213], v[82:83], v[158:159], v[212:213]
	v_fma_f32 v214, |v206|, s6, 1.0
	v_fma_f32 v215, |v207|, s6, 1.0
	v_pk_mul_f32 v[218:219], v[206:207], v[206:207]
	s_nop 0
	v_pk_mul_f32 v[218:219], v[218:219], s[36:37] op_sel_hi:[1,0]
	v_rcp_f32_e32 v214, v214
	v_rcp_f32_e32 v215, v215
	v_exp_f32_e32 v218, v218
	v_exp_f32_e32 v219, v219
	v_pk_fma_f32 v[216:217], v[214:215], s[24:25], v[186:187] op_sel_hi:[1,0,0]
	v_max_f32_e32 v220, 0, v206
	v_pk_fma_f32 v[216:217], v[214:215], v[216:217], s[28:29] op_sel_hi:[1,1,0]
	v_max_f32_e32 v221, 0, v207
	v_pk_fma_f32 v[216:217], v[214:215], v[216:217], s[30:31] op_sel_hi:[1,1,0]
	s_nop 0
	v_pk_fma_f32 v[216:217], v[214:215], v[216:217], s[34:35] op_sel_hi:[1,1,0]
	s_nop 0
	v_pk_mul_f32 v[216:217], v[214:215], v[216:217]
	s_nop 0
	v_pk_mul_f32 v[216:217], v[218:219], v[216:217]
	s_nop 0
	v_fma_f32 v206, -|v206|, v216, v220
	v_fma_f32 v207, -|v207|, v217, v221
	v_mul_f32_e32 v206, v210, v206
	v_mul_f32_e32 v207, v211, v207
	v_fma_f32 v214, |v208|, s6, 1.0
	v_fma_f32 v215, |v209|, s6, 1.0
	v_pk_mul_f32 v[218:219], v[208:209], v[208:209]
	s_nop 0
	v_pk_mul_f32 v[218:219], v[218:219], s[36:37] op_sel_hi:[1,0]
	v_rcp_f32_e32 v214, v214
	v_rcp_f32_e32 v215, v215
	v_exp_f32_e32 v218, v218
	v_exp_f32_e32 v219, v219
	v_pk_fma_f32 v[216:217], v[214:215], s[24:25], v[186:187] op_sel_hi:[1,0,0]
	v_max_f32_e32 v220, 0, v208
	v_pk_fma_f32 v[216:217], v[214:215], v[216:217], s[28:29] op_sel_hi:[1,1,0]
	v_max_f32_e32 v221, 0, v209
	v_pk_fma_f32 v[216:217], v[214:215], v[216:217], s[30:31] op_sel_hi:[1,1,0]
	s_nop 0
	v_pk_fma_f32 v[216:217], v[214:215], v[216:217], s[34:35] op_sel_hi:[1,1,0]
	s_nop 0
	v_pk_mul_f32 v[216:217], v[214:215], v[216:217]
	s_nop 0
	v_pk_mul_f32 v[216:217], v[218:219], v[216:217]
	s_nop 0
	v_fma_f32 v208, -|v208|, v216, v220
	v_fma_f32 v209, -|v209|, v217, v221
	v_mul_f32_e32 v208, v212, v208
	v_mul_f32_e32 v209, v213, v209
	v_cvt_pk_bf16_f32 v190, v206, v207
	v_cvt_pk_bf16_f32 v191, v208, v209
	s_and_saveexec_b64 s[22:23], s[74:75]
	s_cbranch_execz .Lmy_p5_2
	s_lshr_b32 s18, s16, 6
	s_add_i32 s18, s18, 0
	s_mul_i32 s18, s18, 0x5800
	s_mov_b32 s19, 0
	v_lshlrev_b64 v[214:215], 2, v[182:183]
	v_lshl_add_u64 v[214:215], s[18:19], 0, v[214:215]
	v_lshl_add_u64 v[214:215], s[92:93], 0, v[214:215]
	global_store_dwordx4 v[214:215], v[160:163], off
	v_lshl_add_u64 v[216:217], v[214:215], 0, s[52:53]
	global_store_dwordx4 v[216:217], v[156:159], off offset:3072
; __device__ __forceinline__ unsigned cvt_pk_bf16(float lo, float hi) { unsigned r; asm volatile("v_cvt_pk_bf16_f32 %0, %1, %2" : "=v"(r) : "v"(lo), "v"(hi)); return r; }
; __device__ __forceinline__ float ror1(float x) { return __builtin_bit_cast(float, __builtin_amdgcn_update_dpp(0, __builtin_bit_cast(int, x), 0x121, 0xf, 0xf, false)); }
; __device__ __forceinline__ f32x2 gelu_pk(f32x2 v) {
;     const f32x2 av = __builtin_elementwise_abs(v), d = av * 0.2316418882f + 1.0f;
;     f32x2 t; t.x = __builtin_amdgcn_rcpf(d.x); t.y = __builtin_amdgcn_rcpf(d.y);
;     f32x2 q = t * 0.5307027145f + (-0.7265760135f); q = q * t + 0.7107068705f; q = q * t + (-0.142248368f); q = q * t + 0.127414796f; q = q * t;
;     const f32x2 s = (v * v) * (-0.72134752044f);
;     f32x2 e; e.x = __builtin_amdgcn_exp2f(s.x); e.y = __builtin_amdgcn_exp2f(s.y);
;     const f32x2 m = v * (q * e), r = v - m;
;     f32x2 o; o.x = v.x < 0.f ? m.x : r.x; o.y = v.y < 0.f ? m.y : r.y; return o;
; }
;     __device__ __forceinline__ void operator()(AccT& acc, const Unit& u, int wr, int wc, int fr, int fq) const {
;     ...
;                     const f32x4 cg_ = acc[ai][0][m][n], cv_ = acc[ai][1][m][n];
;                     f32x4 p1g, p2g, p1v, p2v;
; #pragma unroll
;                     for (int j = 0; j < 4; ++j) {
;                         p1g[j] = ror1(fr == 15 ? hg[j] : cg_[j]); p2g[j] = ror2(fr >= 14 ? hg[j] : cg_[j]);
;                         p1v[j] = ror1(fr == 15 ? hv[j] : cv_[j]); p2v[j] = ror2(fr >= 14 ? hv[j] : cv_[j]);
;                     }
;                     const f32x4 hcg = bg + w0g * p2g + w1g * p1g + w2g * cg_;
;                     const f32x4 hcv = bv + w0v * p2v + w1v * p1v + w2v * cv_;
;                     const f32x2 ga = gelu_pk((f32x2){hcg[0], hcg[1]}), gb2 = gelu_pk((f32x2){hcg[2], hcg[3]});
;                     u32x2 w; w.x = cvt_pk_bf16(ga.x * hcv[0], ga.y * hcv[1]); w.y = cvt_pk_bf16(gb2.x * hcv[2], gb2.y * hcv[3]);
;                     const int t = tstart + rl;
;                     if (n == 0) stash[ai][m] = w;
;                     else if (rl >= 2) *(u32x4*)(U + (size_t)(arow0 + rl) * FF + colg0) = (u32x4){stash[ai][m].x, stash[ai][m].y, w.x, w.y};
;                     if (rl < 2 || rl >= 254) { float* hp = halo + ((size_t)u.pm * 4 + (rl < 2 ? rl : rl - 252)) * FF2; *(f32x4*)(hp + colg) = cg_; *(f32x4*)(hp + colv) = cv_; }
.Lmy_p5_2:
	s_or_b64 exec, exec, s[22:23]
	v_pk_fma_f32 v[206:207], v[102:103], v[164:165], v[98:99]
	v_pk_fma_f32 v[210:211], v[92:93], v[168:169], v[84:85]
	v_pk_fma_f32 v[208:209], v[104:105], v[166:167], v[100:101]
	v_pk_fma_f32 v[212:213], v[94:95], v[170:171], v[86:87]
	v_pk_fma_f32 v[206:207], v[106:107], v[160:161], v[206:207]
	v_pk_fma_f32 v[210:211], v[88:89], v[156:157], v[210:211]
	v_pk_fma_f32 v[208:209], v[108:109], v[162:163], v[208:209]
	v_pk_fma_f32 v[212:213], v[90:91], v[158:159], v[212:213]
	v_pk_fma_f32 v[206:207], v[110:111], v[144:145], v[206:207]
	v_pk_fma_f32 v[210:211], v[80:81], v[118:119], v[210:211]
	v_pk_fma_f32 v[208:209], v[112:113], v[146:147], v[208:209]
	v_pk_fma_f32 v[212:213], v[82:83], v[120:121], v[212:213]
	v_fma_f32 v214, |v206|, s6, 1.0
	v_fma_f32 v215, |v207|, s6, 1.0
	v_pk_mul_f32 v[218:219], v[206:207], v[206:207]
	s_nop 0
	v_pk_mul_f32 v[218:219], v[218:219], s[36:37] op_sel_hi:[1,0]
	v_rcp_f32_e32 v214, v214
	v_rcp_f32_e32 v215, v215
	v_exp_f32_e32 v218, v218
	v_exp_f32_e32 v219, v219
	v_pk_fma_f32 v[216:217], v[214:215], s[24:25], v[186:187] op_sel_hi:[1,0,0]
	v_max_f32_e32 v220, 0, v206
	v_pk_fma_f32 v[216:217], v[214:215], v[216:217], s[28:29] op_sel_hi:[1,1,0]
	v_max_f32_e32 v221, 0, v207
	v_pk_fma_f32 v[216:217], v[214:215], v[216:217], s[30:31] op_sel_hi:[1,1,0]
	s_nop 0
	v_pk_fma_f32 v[216:217], v[214:215], v[216:217], s[34:35] op_sel_hi:[1,1,0]
	s_nop 0
	v_pk_mul_f32 v[216:217], v[214:215], v[216:217]
	s_nop 0
	v_pk_mul_f32 v[216:217], v[218:219], v[216:217]
	s_nop 0
	v_fma_f32 v206, -|v206|, v216, v220
	v_fma_f32 v207, -|v207|, v217, v221
	v_mul_f32_e32 v206, v210, v206
	v_mul_f32_e32 v207, v211, v207
	v_fma_f32 v214, |v208|, s6, 1.0
	v_fma_f32 v215, |v209|, s6, 1.0
	v_pk_mul_f32 v[218:219], v[208:209], v[208:209]
	s_nop 0
	v_pk_mul_f32 v[218:219], v[218:219], s[36:37] op_sel_hi:[1,0]
	v_rcp_f32_e32 v214, v214
	v_rcp_f32_e32 v215, v215
	v_exp_f32_e32 v218, v218
	v_exp_f32_e32 v219, v219
	v_pk_fma_f32 v[216:217], v[214:215], s[24:25], v[186:187] op_sel_hi:[1,0,0]
	v_max_f32_e32 v220, 0, v208
	v_pk_fma_f32 v[216:217], v[214:215], v[216:217], s[28:29] op_sel_hi:[1,1,0]
	v_max_f32_e32 v221, 0, v209
	v_pk_fma_f32 v[216:217], v[214:215], v[216:217], s[30:31] op_sel_hi:[1,1,0]
	s_nop 0
	v_pk_fma_f32 v[216:217], v[214:215], v[216:217], s[34:35] op_sel_hi:[1,1,0]
	s_nop 0
	v_pk_mul_f32 v[216:217], v[214:215], v[216:217]
	s_nop 0
	v_pk_mul_f32 v[216:217], v[218:219], v[216:217]
	s_nop 0
	v_fma_f32 v208, -|v208|, v216, v220
	v_fma_f32 v209, -|v209|, v217, v221
	v_mul_f32_e32 v208, v212, v208
	v_mul_f32_e32 v209, v213, v209
	v_cvt_pk_bf16_f32 v238, v206, v207
	v_cvt_pk_bf16_f32 v239, v208, v209
	s_and_saveexec_b64 s[22:23], s[74:75]
	s_cbranch_execz .Lmy_p5_3
	s_lshr_b32 s18, s16, 6
	s_add_i32 s18, s18, 1
	s_mul_i32 s18, s18, 0x5800
	s_mov_b32 s19, 0
	v_lshlrev_b64 v[214:215], 2, v[182:183]
	v_lshl_add_u64 v[214:215], s[18:19], 0, v[214:215]
	v_lshl_add_u64 v[214:215], s[92:93], 0, v[214:215]
	global_store_dwordx4 v[214:215], v[144:147], off
	v_lshl_add_u64 v[216:217], v[214:215], 0, s[52:53]
	global_store_dwordx4 v[216:217], v[118:121], off offset:3072
.Lmy_p5_3:
	s_or_b64 exec, exec, s[22:23]
	v_pk_fma_f32 v[206:207], v[102:103], v[160:161], v[98:99]
	v_pk_fma_f32 v[210:211], v[92:93], v[156:157], v[84:85]
	v_pk_fma_f32 v[208:209], v[104:105], v[162:163], v[100:101]
	v_pk_fma_f32 v[212:213], v[94:95], v[158:159], v[86:87]
	v_pk_fma_f32 v[206:207], v[106:107], v[144:145], v[206:207]
	v_pk_fma_f32 v[210:211], v[88:89], v[118:119], v[210:211]
	v_pk_fma_f32 v[208:209], v[108:109], v[146:147], v[208:209]
	v_pk_fma_f32 v[212:213], v[90:91], v[120:121], v[212:213]
	v_pk_fma_f32 v[206:207], v[110:111], v[140:141], v[206:207]
	v_pk_fma_f32 v[210:211], v[80:81], v[114:115], v[210:211]
	v_pk_fma_f32 v[208:209], v[112:113], v[142:143], v[208:209]
	v_pk_fma_f32 v[212:213], v[82:83], v[116:117], v[212:213]
	v_fma_f32 v214, |v206|, s6, 1.0
	v_fma_f32 v215, |v207|, s6, 1.0
	v_pk_mul_f32 v[218:219], v[206:207], v[206:207]
	s_nop 0
	v_pk_mul_f32 v[218:219], v[218:219], s[36:37] op_sel_hi:[1,0]
	v_rcp_f32_e32 v214, v214
	v_rcp_f32_e32 v215, v215
	v_exp_f32_e32 v218, v218
	v_exp_f32_e32 v219, v219
	v_pk_fma_f32 v[216:217], v[214:215], s[24:25], v[186:187] op_sel_hi:[1,0,0]
	v_max_f32_e32 v220, 0, v206
	v_pk_fma_f32 v[216:217], v[214:215], v[216:217], s[28:29] op_sel_hi:[1,1,0]
	v_max_f32_e32 v221, 0, v207
	v_pk_fma_f32 v[216:217], v[214:215], v[216:217], s[30:31] op_sel_hi:[1,1,0]
	s_nop 0
	v_pk_fma_f32 v[216:217], v[214:215], v[216:217], s[34:35] op_sel_hi:[1,1,0]
	s_nop 0
	v_pk_mul_f32 v[216:217], v[214:215], v[216:217]
	s_nop 0
	v_pk_mul_f32 v[216:217], v[218:219], v[216:217]
	s_nop 0
	v_fma_f32 v206, -|v206|, v216, v220
	v_fma_f32 v207, -|v207|, v217, v221
	v_mul_f32_e32 v206, v210, v206
	v_mul_f32_e32 v207, v211, v207
	v_fma_f32 v214, |v208|, s6, 1.0
	v_fma_f32 v215, |v209|, s6, 1.0
	v_pk_mul_f32 v[218:219], v[208:209], v[208:209]
	s_nop 0
	v_pk_mul_f32 v[218:219], v[218:219], s[36:37] op_sel_hi:[1,0]
	v_rcp_f32_e32 v214, v214
	v_rcp_f32_e32 v215, v215
	v_exp_f32_e32 v218, v218
	v_exp_f32_e32 v219, v219
	v_pk_fma_f32 v[216:217], v[214:215], s[24:25], v[186:187] op_sel_hi:[1,0,0]
	v_max_f32_e32 v220, 0, v208
	v_pk_fma_f32 v[216:217], v[214:215], v[216:217], s[28:29] op_sel_hi:[1,1,0]
	v_max_f32_e32 v221, 0, v209
	v_pk_fma_f32 v[216:217], v[214:215], v[216:217], s[30:31] op_sel_hi:[1,1,0]
	s_nop 0
	v_pk_fma_f32 v[216:217], v[214:215], v[216:217], s[34:35] op_sel_hi:[1,1,0]
	s_nop 0
	v_pk_mul_f32 v[216:217], v[214:215], v[216:217]
	s_nop 0
	v_pk_mul_f32 v[216:217], v[218:219], v[216:217]
	s_nop 0
; #define LAS __attribute__((address_space(3)))
; __device__ __forceinline__ unsigned cvt_pk_bf16(float lo, float hi) { unsigned r; asm volatile("v_cvt_pk_bf16_f32 %0, %1, %2" : "=v"(r) : "v"(lo), "v"(hi)); return r; }
; __device__ __forceinline__ f32x2 gelu_pk(f32x2 v) {
;     const f32x2 av = __builtin_elementwise_abs(v), d = av * 0.2316418882f + 1.0f;
;     f32x2 t; t.x = __builtin_amdgcn_rcpf(d.x); t.y = __builtin_amdgcn_rcpf(d.y);
;     f32x2 q = t * 0.5307027145f + (-0.7265760135f); q = q * t + 0.7107068705f; q = q * t + (-0.142248368f); q = q * t + 0.127414796f; q = q * t;
;     const f32x2 s = (v * v) * (-0.72134752044f);
;     f32x2 e; e.x = __builtin_amdgcn_exp2f(s.x); e.y = __builtin_amdgcn_exp2f(s.y);
;     const f32x2 m = v * (q * e), r = v - m;
;     f32x2 o; o.x = v.x < 0.f ? m.x : r.x; o.y = v.y < 0.f ? m.y : r.y; return o;
; }
;     __device__ __forceinline__ void operator()(AccT& acc, const Unit& u, int wr, int wc, int fr, int fq) const {
;     ...
;                 f32x4 hg = (f32x4){0.f, 0.f, 0.f, 0.f}, hv = hg;
;                 const int s = ai * 2 + wr;
;                 if (s > 0 && fr >= 14) {
;                     hg = *(const LAS f32x4*)(xch + (((s - 1) * 2 + (fr - 14)) * 256 + wc * 32 + fq * 8 + n * 4));
;                     hv = *(const LAS f32x4*)(xch + (((s - 1) * 2 + (fr - 14)) * 256 + 128 + wc * 32 + fq * 8 + n * 4));
;                 }
; #pragma unroll
;                 for (int m = 0; m < 4; ++m) {
;                     const int rl = ai * 128 + wr * 64 + m * 16 + fr;
;                     const f32x4 cg_ = acc[ai][0][m][n], cv_ = acc[ai][1][m][n];
;                     f32x4 p1g, p2g, p1v, p2v;
; #pragma unroll
;                     for (int j = 0; j < 4; ++j) {
;                         p1g[j] = ror1(fr == 15 ? hg[j] : cg_[j]); p2g[j] = ror2(fr >= 14 ? hg[j] : cg_[j]);
;                         p1v[j] = ror1(fr == 15 ? hv[j] : cv_[j]); p2v[j] = ror2(fr >= 14 ? hv[j] : cv_[j]);
;                     }
;                     const f32x4 hcg = bg + w0g * p2g + w1g * p1g + w2g * cg_;
;                     const f32x4 hcv = bv + w0v * p2v + w1v * p1v + w2v * cv_;
;                     const f32x2 ga = gelu_pk((f32x2){hcg[0], hcg[1]}), gb2 = gelu_pk((f32x2){hcg[2], hcg[3]});
;                     u32x2 w; w.x = cvt_pk_bf16(ga.x * hcv[0], ga.y * hcv[1]); w.y = cvt_pk_bf16(gb2.x * hcv[2], gb2.y * hcv[3]);
	v_fma_f32 v208, -|v208|, v216, v220
	v_fma_f32 v209, -|v209|, v217, v221
	v_mul_f32_e32 v208, v212, v208
	v_mul_f32_e32 v209, v213, v209
	v_cvt_pk_bf16_f32 v160, v206, v207
	v_cvt_pk_bf16_f32 v161, v208, v209
	v_pk_fma_f32 v[206:207], v[102:103], v[144:145], v[98:99]
	v_pk_fma_f32 v[210:211], v[92:93], v[118:119], v[84:85]
	v_pk_fma_f32 v[208:209], v[104:105], v[146:147], v[100:101]
	v_pk_fma_f32 v[212:213], v[94:95], v[120:121], v[86:87]
	v_pk_fma_f32 v[206:207], v[106:107], v[140:141], v[206:207]
	v_pk_fma_f32 v[210:211], v[88:89], v[114:115], v[210:211]
	v_pk_fma_f32 v[208:209], v[108:109], v[142:143], v[208:209]
	v_pk_fma_f32 v[212:213], v[90:91], v[116:117], v[212:213]
	v_pk_fma_f32 v[206:207], v[110:111], v[152:153], v[206:207]
	v_pk_fma_f32 v[210:211], v[80:81], v[148:149], v[210:211]
	v_pk_fma_f32 v[208:209], v[112:113], v[154:155], v[208:209]
	v_pk_fma_f32 v[212:213], v[82:83], v[150:151], v[212:213]
	v_fma_f32 v214, |v206|, s6, 1.0
	v_fma_f32 v215, |v207|, s6, 1.0
	v_pk_mul_f32 v[218:219], v[206:207], v[206:207]
	s_nop 0
	v_pk_mul_f32 v[218:219], v[218:219], s[36:37] op_sel_hi:[1,0]
	v_rcp_f32_e32 v214, v214
	v_rcp_f32_e32 v215, v215
	v_exp_f32_e32 v218, v218
	v_exp_f32_e32 v219, v219
	v_pk_fma_f32 v[216:217], v[214:215], s[24:25], v[186:187] op_sel_hi:[1,0,0]
	v_max_f32_e32 v220, 0, v206
	v_pk_fma_f32 v[216:217], v[214:215], v[216:217], s[28:29] op_sel_hi:[1,1,0]
	v_max_f32_e32 v221, 0, v207
	v_pk_fma_f32 v[216:217], v[214:215], v[216:217], s[30:31] op_sel_hi:[1,1,0]
	s_nop 0
	v_pk_fma_f32 v[216:217], v[214:215], v[216:217], s[34:35] op_sel_hi:[1,1,0]
	s_nop 0
	v_pk_mul_f32 v[216:217], v[214:215], v[216:217]
	s_nop 0
	v_pk_mul_f32 v[216:217], v[218:219], v[216:217]
	s_nop 0
	v_fma_f32 v206, -|v206|, v216, v220
	v_fma_f32 v207, -|v207|, v217, v221
	v_mul_f32_e32 v206, v210, v206
	v_mul_f32_e32 v207, v211, v207
	v_fma_f32 v214, |v208|, s6, 1.0
	v_fma_f32 v215, |v209|, s6, 1.0
	v_pk_mul_f32 v[218:219], v[208:209], v[208:209]
	s_nop 0
	v_pk_mul_f32 v[218:219], v[218:219], s[36:37] op_sel_hi:[1,0]
	v_rcp_f32_e32 v214, v214
	v_rcp_f32_e32 v215, v215
	v_exp_f32_e32 v218, v218
	v_exp_f32_e32 v219, v219
	v_pk_fma_f32 v[216:217], v[214:215], s[24:25], v[186:187] op_sel_hi:[1,0,0]
	v_max_f32_e32 v220, 0, v208
	v_pk_fma_f32 v[216:217], v[214:215], v[216:217], s[28:29] op_sel_hi:[1,1,0]
	v_max_f32_e32 v221, 0, v209
	v_pk_fma_f32 v[216:217], v[214:215], v[216:217], s[30:31] op_sel_hi:[1,1,0]
	s_nop 0
	v_pk_fma_f32 v[216:217], v[214:215], v[216:217], s[34:35] op_sel_hi:[1,1,0]
	s_nop 0
	v_pk_mul_f32 v[216:217], v[214:215], v[216:217]
	s_nop 0
	v_pk_mul_f32 v[216:217], v[218:219], v[216:217]
	s_nop 0
	v_fma_f32 v208, -|v208|, v216, v220
	v_fma_f32 v209, -|v209|, v217, v221
	v_mul_f32_e32 v208, v212, v208
	v_mul_f32_e32 v209, v213, v209
	v_cvt_pk_bf16_f32 v144, v206, v207
	v_cvt_pk_bf16_f32 v145, v208, v209
	v_mov_b64_e32 v[164:165], 0
	v_mov_b64_e32 v[166:167], 0
	v_mov_b64_e32 v[168:169], 0
	v_mov_b64_e32 v[170:171], 0
	v_mov_b64_e32 v[234:235], 0
	v_mov_b64_e32 v[236:237], 0
	v_mov_b64_e32 v[250:251], 0
	v_mov_b64_e32 v[252:253], 0
	s_and_saveexec_b64 s[20:21], s[48:49]
	s_cbranch_execz .Lmy_p5_4
	ds_read_b128 v[234:237], v188 offset:4096
	ds_read_b128 v[250:253], v188 offset:4112
	ds_read_b128 v[164:167], v188 offset:4160
	ds_read_b128 v[168:171], v188 offset:4176
.Lmy_p5_4:
	s_or_b64 exec, exec, s[20:21]
	s_waitcnt lgkmcnt(0)
	s_nop 4
	v_mov_b32_dpp v214, v122 row_ror:1 row_mask:0xf bank_mask:0xf
	v_mov_b32_dpp v215, v123 row_ror:1 row_mask:0xf bank_mask:0xf
	v_mov_b32_dpp v216, v124 row_ror:1 row_mask:0xf bank_mask:0xf
	v_mov_b32_dpp v217, v125 row_ror:1 row_mask:0xf bank_mask:0xf
	s_nop 1
	v_cndmask_b32_e64 v164, v214, v164, s[48:49]
	v_cndmask_b32_e64 v165, v215, v165, s[48:49]
	v_cndmask_b32_e64 v166, v216, v166, s[48:49]
	v_cndmask_b32_e64 v167, v217, v167, s[48:49]
	v_mov_b32_dpp v214, v128 row_ror:1 row_mask:0xf bank_mask:0xf
	v_mov_b32_dpp v215, v129 row_ror:1 row_mask:0xf bank_mask:0xf
	v_mov_b32_dpp v216, v130 row_ror:1 row_mask:0xf bank_mask:0xf
	v_mov_b32_dpp v217, v131 row_ror:1 row_mask:0xf bank_mask:0xf
	s_nop 1
	v_cndmask_b32_e64 v168, v214, v168, s[48:49]
	v_cndmask_b32_e64 v169, v215, v169, s[48:49]
	v_cndmask_b32_e64 v170, v216, v170, s[48:49]
	v_cndmask_b32_e64 v171, v217, v171, s[48:49]
	v_mov_b32_dpp v214, v68 row_ror:1 row_mask:0xf bank_mask:0xf
	v_mov_b32_dpp v215, v69 row_ror:1 row_mask:0xf bank_mask:0xf
	v_mov_b32_dpp v216, v70 row_ror:1 row_mask:0xf bank_mask:0xf
	v_mov_b32_dpp v217, v71 row_ror:1 row_mask:0xf bank_mask:0xf
	s_nop 1
	v_cndmask_b32_e64 v234, v214, v234, s[48:49]
	v_cndmask_b32_e64 v235, v215, v235, s[48:49]
	v_cndmask_b32_e64 v236, v216, v236, s[48:49]
	v_cndmask_b32_e64 v237, v217, v237, s[48:49]
	v_mov_b32_dpp v214, v64 row_ror:1 row_mask:0xf bank_mask:0xf
	v_mov_b32_dpp v215, v65 row_ror:1 row_mask:0xf bank_mask:0xf
	v_mov_b32_dpp v216, v66 row_ror:1 row_mask:0xf bank_mask:0xf
	v_mov_b32_dpp v217, v67 row_ror:1 row_mask:0xf bank_mask:0xf
	s_nop 1
	v_cndmask_b32_e64 v250, v214, v250, s[48:49]
	v_cndmask_b32_e64 v251, v215, v251, s[48:49]
	v_cndmask_b32_e64 v252, v216, v252, s[48:49]
	v_cndmask_b32_e64 v253, v217, v253, s[48:49]
	v_pk_fma_f32 v[206:207], v[102:103], v[234:235], v[98:99]
	v_pk_fma_f32 v[210:211], v[92:93], v[250:251], v[84:85]
	v_pk_fma_f32 v[208:209], v[104:105], v[236:237], v[100:101]
	v_pk_fma_f32 v[212:213], v[94:95], v[252:253], v[86:87]
	v_pk_fma_f32 v[206:207], v[106:107], v[164:165], v[206:207]
	v_pk_fma_f32 v[210:211], v[88:89], v[168:169], v[210:211]
	v_pk_fma_f32 v[208:209], v[108:109], v[166:167], v[208:209]
	v_pk_fma_f32 v[212:213], v[90:91], v[170:171], v[212:213]
; __device__ __forceinline__ unsigned cvt_pk_bf16(float lo, float hi) { unsigned r; asm volatile("v_cvt_pk_bf16_f32 %0, %1, %2" : "=v"(r) : "v"(lo), "v"(hi)); return r; }
; __device__ __forceinline__ float ror1(float x) { return __builtin_bit_cast(float, __builtin_amdgcn_update_dpp(0, __builtin_bit_cast(int, x), 0x121, 0xf, 0xf, false)); }
; __device__ __forceinline__ float ror2(float x) { return __builtin_bit_cast(float, __builtin_amdgcn_update_dpp(0, __builtin_bit_cast(int, x), 0x122, 0xf, 0xf, false)); }
; __device__ __forceinline__ f32x2 gelu_pk(f32x2 v) {
;     const f32x2 av = __builtin_elementwise_abs(v), d = av * 0.2316418882f + 1.0f;
;     f32x2 t; t.x = __builtin_amdgcn_rcpf(d.x); t.y = __builtin_amdgcn_rcpf(d.y);
;     f32x2 q = t * 0.5307027145f + (-0.7265760135f); q = q * t + 0.7107068705f; q = q * t + (-0.142248368f); q = q * t + 0.127414796f; q = q * t;
;     const f32x2 s = (v * v) * (-0.72134752044f);
;     f32x2 e; e.x = __builtin_amdgcn_exp2f(s.x); e.y = __builtin_amdgcn_exp2f(s.y);
;     const f32x2 m = v * (q * e), r = v - m;
;     f32x2 o; o.x = v.x < 0.f ? m.x : r.x; o.y = v.y < 0.f ? m.y : r.y; return o;
;     __device__ __forceinline__ void operator()(AccT& acc, const Unit& u, int wr, int wc, int fr, int fq) const {
;     ...
;                 for (int m = 0; m < 4; ++m) {
;                     const int rl = ai * 128 + wr * 64 + m * 16 + fr;
;                     const f32x4 cg_ = acc[ai][0][m][n], cv_ = acc[ai][1][m][n];
;                     f32x4 p1g, p2g, p1v, p2v;
; #pragma unroll
;                     for (int j = 0; j < 4; ++j) {
;                         p1g[j] = ror1(fr == 15 ? hg[j] : cg_[j]); p2g[j] = ror2(fr >= 14 ? hg[j] : cg_[j]);
;                         p1v[j] = ror1(fr == 15 ? hv[j] : cv_[j]); p2v[j] = ror2(fr >= 14 ? hv[j] : cv_[j]);
;                     }
;                     const f32x4 hcg = bg + w0g * p2g + w1g * p1g + w2g * cg_;
;                     const f32x4 hcv = bv + w0v * p2v + w1v * p1v + w2v * cv_;
;                     const f32x2 ga = gelu_pk((f32x2){hcg[0], hcg[1]}), gb2 = gelu_pk((f32x2){hcg[2], hcg[3]});
;                     u32x2 w; w.x = cvt_pk_bf16(ga.x * hcv[0], ga.y * hcv[1]); w.y = cvt_pk_bf16(gb2.x * hcv[2], gb2.y * hcv[3]);
;                     const int t = tstart + rl;
;                     if (n == 0) stash[ai][m] = w;
	v_pk_fma_f32 v[206:207], v[110:111], v[136:137], v[206:207]
	v_pk_fma_f32 v[210:211], v[80:81], v[132:133], v[210:211]
	v_pk_fma_f32 v[208:209], v[112:113], v[138:139], v[208:209]
	v_pk_fma_f32 v[212:213], v[82:83], v[134:135], v[212:213]
	v_fma_f32 v214, |v206|, s6, 1.0
	v_fma_f32 v215, |v207|, s6, 1.0
	v_pk_mul_f32 v[218:219], v[206:207], v[206:207]
	s_nop 0
	v_pk_mul_f32 v[218:219], v[218:219], s[36:37] op_sel_hi:[1,0]
	v_rcp_f32_e32 v214, v214
	v_rcp_f32_e32 v215, v215
	v_exp_f32_e32 v218, v218
	v_exp_f32_e32 v219, v219
	v_pk_fma_f32 v[216:217], v[214:215], s[24:25], v[186:187] op_sel_hi:[1,0,0]
	v_max_f32_e32 v220, 0, v206
	v_pk_fma_f32 v[216:217], v[214:215], v[216:217], s[28:29] op_sel_hi:[1,1,0]
	v_max_f32_e32 v221, 0, v207
	v_pk_fma_f32 v[216:217], v[214:215], v[216:217], s[30:31] op_sel_hi:[1,1,0]
	s_nop 0
	v_pk_fma_f32 v[216:217], v[214:215], v[216:217], s[34:35] op_sel_hi:[1,1,0]
	s_nop 0
	v_pk_mul_f32 v[216:217], v[214:215], v[216:217]
	s_nop 0
	v_pk_mul_f32 v[216:217], v[218:219], v[216:217]
	s_nop 0
	v_fma_f32 v206, -|v206|, v216, v220
	v_fma_f32 v207, -|v207|, v217, v221
	v_mul_f32_e32 v206, v210, v206
	v_mul_f32_e32 v207, v211, v207
	v_fma_f32 v214, |v208|, s6, 1.0
	v_fma_f32 v215, |v209|, s6, 1.0
	v_pk_mul_f32 v[218:219], v[208:209], v[208:209]
	s_nop 0
	v_pk_mul_f32 v[218:219], v[218:219], s[36:37] op_sel_hi:[1,0]
	v_rcp_f32_e32 v214, v214
	v_rcp_f32_e32 v215, v215
	v_exp_f32_e32 v218, v218
	v_exp_f32_e32 v219, v219
	v_pk_fma_f32 v[216:217], v[214:215], s[24:25], v[186:187] op_sel_hi:[1,0,0]
	v_max_f32_e32 v220, 0, v208
	v_pk_fma_f32 v[216:217], v[214:215], v[216:217], s[28:29] op_sel_hi:[1,1,0]
	v_max_f32_e32 v221, 0, v209
	v_pk_fma_f32 v[216:217], v[214:215], v[216:217], s[30:31] op_sel_hi:[1,1,0]
	s_nop 0
	v_pk_fma_f32 v[216:217], v[214:215], v[216:217], s[34:35] op_sel_hi:[1,1,0]
	s_nop 0
	v_pk_mul_f32 v[216:217], v[214:215], v[216:217]
	s_nop 0
	v_pk_mul_f32 v[216:217], v[218:219], v[216:217]
	s_nop 0
	v_fma_f32 v208, -|v208|, v216, v220
	v_fma_f32 v209, -|v209|, v217, v221
	v_mul_f32_e32 v208, v212, v208
	v_mul_f32_e32 v209, v213, v209
	v_cvt_pk_bf16_f32 v156, v206, v207
	v_cvt_pk_bf16_f32 v157, v208, v209
	v_pk_fma_f32 v[206:207], v[102:103], v[164:165], v[98:99]
	v_pk_fma_f32 v[210:211], v[92:93], v[168:169], v[84:85]
	v_pk_fma_f32 v[208:209], v[104:105], v[166:167], v[100:101]
	v_pk_fma_f32 v[212:213], v[94:95], v[170:171], v[86:87]
	v_pk_fma_f32 v[206:207], v[106:107], v[136:137], v[206:207]
	v_pk_fma_f32 v[210:211], v[88:89], v[132:133], v[210:211]
	v_pk_fma_f32 v[208:209], v[108:109], v[138:139], v[208:209]
	v_pk_fma_f32 v[212:213], v[90:91], v[134:135], v[212:213]
	v_pk_fma_f32 v[206:207], v[110:111], v[76:77], v[206:207]
	v_pk_fma_f32 v[210:211], v[80:81], v[72:73], v[210:211]
	v_pk_fma_f32 v[208:209], v[112:113], v[78:79], v[208:209]
	v_pk_fma_f32 v[212:213], v[82:83], v[74:75], v[212:213]
	v_fma_f32 v214, |v206|, s6, 1.0
	v_fma_f32 v215, |v207|, s6, 1.0
	v_pk_mul_f32 v[218:219], v[206:207], v[206:207]
	s_nop 0
	v_pk_mul_f32 v[218:219], v[218:219], s[36:37] op_sel_hi:[1,0]
	v_rcp_f32_e32 v214, v214
	v_rcp_f32_e32 v215, v215
	v_exp_f32_e32 v218, v218
	v_exp_f32_e32 v219, v219
	v_pk_fma_f32 v[216:217], v[214:215], s[24:25], v[186:187] op_sel_hi:[1,0,0]
	v_max_f32_e32 v220, 0, v206
	v_pk_fma_f32 v[216:217], v[214:215], v[216:217], s[28:29] op_sel_hi:[1,1,0]
	v_max_f32_e32 v221, 0, v207
	v_pk_fma_f32 v[216:217], v[214:215], v[216:217], s[30:31] op_sel_hi:[1,1,0]
	s_nop 0
	v_pk_fma_f32 v[216:217], v[214:215], v[216:217], s[34:35] op_sel_hi:[1,1,0]
	s_nop 0
	v_pk_mul_f32 v[216:217], v[214:215], v[216:217]
	s_nop 0
	v_pk_mul_f32 v[216:217], v[218:219], v[216:217]
	s_nop 0
	v_fma_f32 v206, -|v206|, v216, v220
	v_fma_f32 v207, -|v207|, v217, v221
	v_mul_f32_e32 v206, v210, v206
	v_mul_f32_e32 v207, v211, v207
	v_fma_f32 v214, |v208|, s6, 1.0
	v_fma_f32 v215, |v209|, s6, 1.0
	v_pk_mul_f32 v[218:219], v[208:209], v[208:209]
	s_nop 0
	v_pk_mul_f32 v[218:219], v[218:219], s[36:37] op_sel_hi:[1,0]
	v_rcp_f32_e32 v214, v214
	v_rcp_f32_e32 v215, v215
	v_exp_f32_e32 v218, v218
	v_exp_f32_e32 v219, v219
	v_pk_fma_f32 v[216:217], v[214:215], s[24:25], v[186:187] op_sel_hi:[1,0,0]
	v_max_f32_e32 v220, 0, v208
	v_pk_fma_f32 v[216:217], v[214:215], v[216:217], s[28:29] op_sel_hi:[1,1,0]
	v_max_f32_e32 v221, 0, v209
	v_pk_fma_f32 v[216:217], v[214:215], v[216:217], s[30:31] op_sel_hi:[1,1,0]
	s_nop 0
	v_pk_fma_f32 v[216:217], v[214:215], v[216:217], s[34:35] op_sel_hi:[1,1,0]
	s_nop 0
	v_pk_mul_f32 v[216:217], v[214:215], v[216:217]
	s_nop 0
	v_pk_mul_f32 v[216:217], v[218:219], v[216:217]
	s_nop 0
	v_fma_f32 v208, -|v208|, v216, v220
	v_fma_f32 v209, -|v209|, v217, v221
	v_mul_f32_e32 v208, v212, v208
	v_mul_f32_e32 v209, v213, v209
	v_cvt_pk_bf16_f32 v118, v206, v207
	v_cvt_pk_bf16_f32 v119, v208, v209
	v_pk_fma_f32 v[206:207], v[102:103], v[136:137], v[98:99]
	v_pk_fma_f32 v[210:211], v[92:93], v[132:133], v[84:85]
	v_pk_fma_f32 v[208:209], v[104:105], v[138:139], v[100:101]
	v_pk_fma_f32 v[212:213], v[94:95], v[134:135], v[86:87]
	v_pk_fma_f32 v[206:207], v[106:107], v[76:77], v[206:207]
	v_pk_fma_f32 v[210:211], v[88:89], v[72:73], v[210:211]
	v_pk_fma_f32 v[208:209], v[108:109], v[78:79], v[208:209]
	v_pk_fma_f32 v[212:213], v[90:91], v[74:75], v[212:213]
	v_pk_fma_f32 v[206:207], v[110:111], v[68:69], v[206:207]
	v_pk_fma_f32 v[210:211], v[80:81], v[64:65], v[210:211]
	v_pk_fma_f32 v[208:209], v[112:113], v[70:71], v[208:209]
	v_pk_fma_f32 v[212:213], v[82:83], v[66:67], v[212:213]
	v_fma_f32 v214, |v206|, s6, 1.0
	v_fma_f32 v215, |v207|, s6, 1.0
	v_pk_mul_f32 v[218:219], v[206:207], v[206:207]
	s_nop 0
; __device__ __forceinline__ unsigned cvt_pk_bf16(float lo, float hi) { unsigned r; asm volatile("v_cvt_pk_bf16_f32 %0, %1, %2" : "=v"(r) : "v"(lo), "v"(hi)); return r; }
; __device__ __forceinline__ float ror1(float x) { return __builtin_bit_cast(float, __builtin_amdgcn_update_dpp(0, __builtin_bit_cast(int, x), 0x121, 0xf, 0xf, false)); }
; __device__ __forceinline__ f32x2 gelu_pk(f32x2 v) {
;     const f32x2 av = __builtin_elementwise_abs(v), d = av * 0.2316418882f + 1.0f;
;     f32x2 t; t.x = __builtin_amdgcn_rcpf(d.x); t.y = __builtin_amdgcn_rcpf(d.y);
;     f32x2 q = t * 0.5307027145f + (-0.7265760135f); q = q * t + 0.7107068705f; q = q * t + (-0.142248368f); q = q * t + 0.127414796f; q = q * t;
;     const f32x2 s = (v * v) * (-0.72134752044f);
;     f32x2 e; e.x = __builtin_amdgcn_exp2f(s.x); e.y = __builtin_amdgcn_exp2f(s.y);
;     const f32x2 m = v * (q * e), r = v - m;
;     f32x2 o; o.x = v.x < 0.f ? m.x : r.x; o.y = v.y < 0.f ? m.y : r.y; return o;
;     __device__ __forceinline__ void operator()(AccT& acc, const Unit& u, int wr, int wc, int fr, int fq) const {
;     ...
;                     for (int j = 0; j < 4; ++j) {
;                         p1g[j] = ror1(fr == 15 ? hg[j] : cg_[j]); p2g[j] = ror2(fr >= 14 ? hg[j] : cg_[j]);
;                         p1v[j] = ror1(fr == 15 ? hv[j] : cv_[j]); p2v[j] = ror2(fr >= 14 ? hv[j] : cv_[j]);
;                     }
;                     const f32x4 hcg = bg + w0g * p2g + w1g * p1g + w2g * cg_;
;                     const f32x4 hcv = bv + w0v * p2v + w1v * p1v + w2v * cv_;
;                     const f32x2 ga = gelu_pk((f32x2){hcg[0], hcg[1]}), gb2 = gelu_pk((f32x2){hcg[2], hcg[3]});
;                     u32x2 w; w.x = cvt_pk_bf16(ga.x * hcv[0], ga.y * hcv[1]); w.y = cvt_pk_bf16(gb2.x * hcv[2], gb2.y * hcv[3]);
;                     const int t = tstart + rl;
;                     if (n == 0) stash[ai][m] = w;
;                     else if (rl >= 2) *(u32x4*)(U + (size_t)(arow0 + rl) * FF + colg0) = (u32x4){stash[ai][m].x, stash[ai][m].y, w.x, w.y};
;                     if (rl < 2 || rl >= 254) { float* hp = halo + ((size_t)u.pm * 4 + (rl < 2 ? rl : rl - 252)) * FF2; *(f32x4*)(hp + colg) = cg_; *(f32x4*)(hp + colv) = cv_; }
;                     if (t >= SEQ - 2) { float* cp = conv_p + (size_t)(b * 2 + (t - (SEQ - 2))) * FF2; *(f32x4*)(cp + colg) = cg_; *(f32x4*)(cp + colv) = cv_; }
	v_pk_mul_f32 v[218:219], v[218:219], s[36:37] op_sel_hi:[1,0]
	v_rcp_f32_e32 v214, v214
	v_rcp_f32_e32 v215, v215
	v_exp_f32_e32 v218, v218
	v_exp_f32_e32 v219, v219
	v_pk_fma_f32 v[216:217], v[214:215], s[24:25], v[186:187] op_sel_hi:[1,0,0]
	v_max_f32_e32 v220, 0, v206
	v_pk_fma_f32 v[216:217], v[214:215], v[216:217], s[28:29] op_sel_hi:[1,1,0]
	v_max_f32_e32 v221, 0, v207
	v_pk_fma_f32 v[216:217], v[214:215], v[216:217], s[30:31] op_sel_hi:[1,1,0]
	s_nop 0
	v_pk_fma_f32 v[216:217], v[214:215], v[216:217], s[34:35] op_sel_hi:[1,1,0]
	s_nop 0
	v_pk_mul_f32 v[216:217], v[214:215], v[216:217]
	s_nop 0
	v_pk_mul_f32 v[216:217], v[218:219], v[216:217]
	s_nop 0
	v_fma_f32 v206, -|v206|, v216, v220
	v_fma_f32 v207, -|v207|, v217, v221
	v_mul_f32_e32 v206, v210, v206
	v_mul_f32_e32 v207, v211, v207
	v_fma_f32 v214, |v208|, s6, 1.0
	v_fma_f32 v215, |v209|, s6, 1.0
	v_pk_mul_f32 v[218:219], v[208:209], v[208:209]
	s_nop 0
	v_pk_mul_f32 v[218:219], v[218:219], s[36:37] op_sel_hi:[1,0]
	v_rcp_f32_e32 v214, v214
	v_rcp_f32_e32 v215, v215
	v_exp_f32_e32 v218, v218
	v_exp_f32_e32 v219, v219
	v_pk_fma_f32 v[216:217], v[214:215], s[24:25], v[186:187] op_sel_hi:[1,0,0]
	v_max_f32_e32 v220, 0, v208
	v_pk_fma_f32 v[216:217], v[214:215], v[216:217], s[28:29] op_sel_hi:[1,1,0]
	v_max_f32_e32 v221, 0, v209
	v_pk_fma_f32 v[216:217], v[214:215], v[216:217], s[30:31] op_sel_hi:[1,1,0]
	s_nop 0
	v_pk_fma_f32 v[216:217], v[214:215], v[216:217], s[34:35] op_sel_hi:[1,1,0]
	s_nop 0
	v_pk_mul_f32 v[216:217], v[214:215], v[216:217]
	s_nop 0
	v_pk_mul_f32 v[216:217], v[218:219], v[216:217]
	s_nop 0
	v_fma_f32 v208, -|v208|, v216, v220
	v_fma_f32 v209, -|v209|, v217, v221
	v_mul_f32_e32 v208, v212, v208
	v_mul_f32_e32 v209, v213, v209
	v_cvt_pk_bf16_f32 v140, v206, v207
	v_cvt_pk_bf16_f32 v141, v208, v209
	s_and_saveexec_b64 s[22:23], s[76:77]
	s_cbranch_execz .Lmy_p5_5
	s_lshr_b32 s18, s16, 6
	s_add_i32 s18, s18, 2
	s_mul_i32 s18, s18, 0x5800
	s_mov_b32 s19, 0
	v_lshlrev_b64 v[214:215], 2, v[182:183]
	v_lshl_add_u64 v[214:215], s[18:19], 0, v[214:215]
	v_lshl_add_u64 v[214:215], s[92:93], 0, v[214:215]
	global_store_dwordx4 v[214:215], v[68:71], off
	v_lshl_add_u64 v[216:217], v[214:215], 0, s[52:53]
	global_store_dwordx4 v[216:217], v[64:67], off offset:3072
	s_bfe_u32 s18, s16, 0x60008
	s_cmp_eq_u32 s18, 63
	s_cbranch_scc0 .Lmy_p5_5
	s_lshr_b32 s18, s16, 14
	s_lshl_b32 s18, s18, 1
	s_add_i32 s18, s18, 0
	s_mul_i32 s18, s18, 0x5800
	s_mov_b32 s19, 0
	v_lshlrev_b64 v[214:215], 2, v[182:183]
	v_lshl_add_u64 v[214:215], s[18:19], 0, v[214:215]
	v_lshl_add_u64 v[214:215], s[0:1], 0, v[214:215]
	global_store_dwordx4 v[214:215], v[68:71], off
	v_lshl_add_u64 v[216:217], v[214:215], 0, s[52:53]
	global_store_dwordx4 v[216:217], v[64:67], off offset:3072
.Lmy_p5_5:
	s_or_b64 exec, exec, s[22:23]
	v_pk_fma_f32 v[206:207], v[102:103], v[76:77], v[98:99]
	v_pk_fma_f32 v[210:211], v[92:93], v[72:73], v[84:85]
	v_pk_fma_f32 v[208:209], v[104:105], v[78:79], v[100:101]
	v_pk_fma_f32 v[212:213], v[94:95], v[74:75], v[86:87]
	v_pk_fma_f32 v[206:207], v[106:107], v[68:69], v[206:207]
	v_pk_fma_f32 v[210:211], v[88:89], v[64:65], v[210:211]
	v_pk_fma_f32 v[208:209], v[108:109], v[70:71], v[208:209]
	v_pk_fma_f32 v[212:213], v[90:91], v[66:67], v[212:213]
	v_pk_fma_f32 v[206:207], v[110:111], v[122:123], v[206:207]
	v_pk_fma_f32 v[210:211], v[80:81], v[128:129], v[210:211]
	v_pk_fma_f32 v[208:209], v[112:113], v[124:125], v[208:209]
	v_pk_fma_f32 v[212:213], v[82:83], v[130:131], v[212:213]
	v_fma_f32 v214, |v206|, s6, 1.0
	v_fma_f32 v215, |v207|, s6, 1.0
	v_pk_mul_f32 v[218:219], v[206:207], v[206:207]
	s_nop 0
	v_pk_mul_f32 v[218:219], v[218:219], s[36:37] op_sel_hi:[1,0]
	v_rcp_f32_e32 v214, v214
	v_rcp_f32_e32 v215, v215
	v_exp_f32_e32 v218, v218
	v_exp_f32_e32 v219, v219
	v_pk_fma_f32 v[216:217], v[214:215], s[24:25], v[186:187] op_sel_hi:[1,0,0]
	v_max_f32_e32 v220, 0, v206
	v_pk_fma_f32 v[216:217], v[214:215], v[216:217], s[28:29] op_sel_hi:[1,1,0]
	v_max_f32_e32 v221, 0, v207
	v_pk_fma_f32 v[216:217], v[214:215], v[216:217], s[30:31] op_sel_hi:[1,1,0]
	s_nop 0
	v_pk_fma_f32 v[216:217], v[214:215], v[216:217], s[34:35] op_sel_hi:[1,1,0]
	s_nop 0
	v_pk_mul_f32 v[216:217], v[214:215], v[216:217]
	s_nop 0
	v_pk_mul_f32 v[216:217], v[218:219], v[216:217]
	s_nop 0
	v_fma_f32 v206, -|v206|, v216, v220
	v_fma_f32 v207, -|v207|, v217, v221
	v_mul_f32_e32 v206, v210, v206
	v_mul_f32_e32 v207, v211, v207
	v_fma_f32 v214, |v208|, s6, 1.0
	v_fma_f32 v215, |v209|, s6, 1.0
	v_pk_mul_f32 v[218:219], v[208:209], v[208:209]
	s_nop 0
	v_pk_mul_f32 v[218:219], v[218:219], s[36:37] op_sel_hi:[1,0]
	v_rcp_f32_e32 v214, v214
	v_rcp_f32_e32 v215, v215
	v_exp_f32_e32 v218, v218
	v_exp_f32_e32 v219, v219
	v_pk_fma_f32 v[216:217], v[214:215], s[24:25], v[186:187] op_sel_hi:[1,0,0]
	v_max_f32_e32 v220, 0, v208
	v_pk_fma_f32 v[216:217], v[214:215], v[216:217], s[28:29] op_sel_hi:[1,1,0]
	v_max_f32_e32 v221, 0, v209
	v_pk_fma_f32 v[216:217], v[214:215], v[216:217], s[30:31] op_sel_hi:[1,1,0]
	s_nop 0
	v_pk_fma_f32 v[216:217], v[214:215], v[216:217], s[34:35] op_sel_hi:[1,1,0]
	s_nop 0
	v_pk_mul_f32 v[216:217], v[214:215], v[216:217]
	s_nop 0
	v_pk_mul_f32 v[216:217], v[218:219], v[216:217]
	s_nop 0
	v_fma_f32 v208, -|v208|, v216, v220
	v_fma_f32 v209, -|v209|, v217, v221
	v_mul_f32_e32 v208, v212, v208
	v_mul_f32_e32 v209, v213, v209
	v_cvt_pk_bf16_f32 v152, v206, v207
	v_cvt_pk_bf16_f32 v153, v208, v209
	s_and_saveexec_b64 s[22:23], s[76:77]
	s_cbranch_execz .Lmy_p5_6
	s_lshr_b32 s18, s16, 6
	s_add_i32 s18, s18, 3
	s_mul_i32 s18, s18, 0x5800
	s_mov_b32 s19, 0
	v_lshlrev_b64 v[214:215], 2, v[182:183]
	v_lshl_add_u64 v[214:215], s[18:19], 0, v[214:215]
	v_lshl_add_u64 v[214:215], s[92:93], 0, v[214:215]
	global_store_dwordx4 v[214:215], v[122:125], off
	v_lshl_add_u64 v[216:217], v[214:215], 0, s[52:53]
	global_store_dwordx4 v[216:217], v[128:131], off offset:3072
	s_bfe_u32 s18, s16, 0x60008
	s_cmp_eq_u32 s18, 63
	s_cbranch_scc0 .Lmy_p5_6
	s_lshr_b32 s18, s16, 14
	s_lshl_b32 s18, s18, 1
	s_add_i32 s18, s18, 1
	s_mul_i32 s18, s18, 0x5800
	s_mov_b32 s19, 0
	v_lshlrev_b64 v[214:215], 2, v[182:183]
	v_lshl_add_u64 v[214:215], s[18:19], 0, v[214:215]
	v_lshl_add_u64 v[214:215], s[0:1], 0, v[214:215]
	global_store_dwordx4 v[214:215], v[122:125], off
	v_lshl_add_u64 v[216:217], v[214:215], 0, s[52:53]
	global_store_dwordx4 v[216:217], v[128:131], off offset:3072

; __device__ __forceinline__ f32x2 gelu_pk(f32x2 v) {
;     const f32x2 av = __builtin_elementwise_abs(v), d = av * 0.2316418882f + 1.0f;
;     f32x2 t; t.x = __builtin_amdgcn_rcpf(d.x); t.y = __builtin_amdgcn_rcpf(d.y);
;     __device__ __forceinline__ void operator()(AccT& acc, const Unit& u, int wr, int wc, int fr, int fq) const {
;     ...
;             for (int ai = 0; ai < 2; ++ai) {
;                 f32x4 hg = (f32x4){0.f, 0.f, 0.f, 0.f}, hv = hg;
;                 const int s = ai * 2 + wr;
;                 if (s > 0 && fr >= 14) {
;                     hg = *(const LAS f32x4*)(xch + (((s - 1) * 2 + (fr - 14)) * 256 + wc * 32 + fq * 8 + n * 4));
;                     hv = *(const LAS f32x4*)(xch + (((s - 1) * 2 + (fr - 14)) * 256 + 128 + wc * 32 + fq * 8 + n * 4));
;                 }
; #pragma unroll
;                 for (int m = 0; m < 4; ++m) {
;                     const int rl = ai * 128 + wr * 64 + m * 16 + fr;
;                     const f32x4 cg_ = acc[ai][0][m][n], cv_ = acc[ai][1][m][n];
;                     f32x4 p1g, p2g, p1v, p2v;
; #pragma unroll
;                     for (int j = 0; j < 4; ++j) {
;                         p1g[j] = ror1(fr == 15 ? hg[j] : cg_[j]); p2g[j] = ror2(fr >= 14 ? hg[j] : cg_[j]);
;                         p1v[j] = ror1(fr == 15 ? hv[j] : cv_[j]); p2v[j] = ror2(fr >= 14 ? hv[j] : cv_[j]);
;                     }
;                     const f32x4 hcg = bg + w0g * p2g + w1g * p1g + w2g * cg_;
;                     const f32x4 hcv = bv + w0v * p2v + w1v * p1v + w2v * cv_;
;                     const f32x2 ga = gelu_pk((f32x2){hcg[0], hcg[1]}), gb2 = gelu_pk((f32x2){hcg[2], hcg[3]});
;                     u32x2 w; w.x = cvt_pk_bf16(ga.x * hcv[0], ga.y * hcv[1]); w.y = cvt_pk_bf16(gb2.x * hcv[2], gb2.y * hcv[3]);
;                     const int t = tstart + rl;
;                     if (n == 0) stash[ai][m] = w;
;                     else if (rl >= 2) *(u32x4*)(U + (size_t)(arow0 + rl) * FF + colg0) = (u32x4){stash[ai][m].x, stash[ai][m].y, w.x, w.y};
;                     if (rl < 2 || rl >= 254) { float* hp = halo + ((size_t)u.pm * 4 + (rl < 2 ? rl : rl - 252)) * FF2; *(f32x4*)(hp + colg) = cg_; *(f32x4*)(hp + colv) = cv_; }
;                     if (t >= SEQ - 2) { float* cp = conv_p + (size_t)(b * 2 + (t - (SEQ - 2))) * FF2; *(f32x4*)(cp + colg) = cg_; *(f32x4*)(cp + colv) = cv_; }
.Lmy_p5_7:
	s_or_b64 exec, exec, s[20:21]
	s_waitcnt lgkmcnt(0)
	s_nop 4
	v_mov_b32_dpp v214, v48 row_ror:1 row_mask:0xf bank_mask:0xf
	v_mov_b32_dpp v215, v49 row_ror:1 row_mask:0xf bank_mask:0xf
	v_mov_b32_dpp v216, v50 row_ror:1 row_mask:0xf bank_mask:0xf
	v_mov_b32_dpp v217, v51 row_ror:1 row_mask:0xf bank_mask:0xf
	s_nop 1
	v_cndmask_b32_e64 v164, v214, v164, s[48:49]
	v_cndmask_b32_e64 v165, v215, v165, s[48:49]
	v_cndmask_b32_e64 v166, v216, v166, s[48:49]
	v_cndmask_b32_e64 v167, v217, v167, s[48:49]
	v_mov_b32_dpp v214, v44 row_ror:1 row_mask:0xf bank_mask:0xf
	v_mov_b32_dpp v215, v45 row_ror:1 row_mask:0xf bank_mask:0xf
	v_mov_b32_dpp v216, v46 row_ror:1 row_mask:0xf bank_mask:0xf
	v_mov_b32_dpp v217, v47 row_ror:1 row_mask:0xf bank_mask:0xf
	s_nop 1
	v_cndmask_b32_e64 v168, v214, v168, s[48:49]
	v_cndmask_b32_e64 v169, v215, v169, s[48:49]
	v_cndmask_b32_e64 v170, v216, v170, s[48:49]
	v_cndmask_b32_e64 v171, v217, v171, s[48:49]
	v_mov_b32_dpp v214, v36 row_ror:1 row_mask:0xf bank_mask:0xf
	v_mov_b32_dpp v215, v37 row_ror:1 row_mask:0xf bank_mask:0xf
	v_mov_b32_dpp v216, v38 row_ror:1 row_mask:0xf bank_mask:0xf
	v_mov_b32_dpp v217, v39 row_ror:1 row_mask:0xf bank_mask:0xf
	s_nop 1
	v_cndmask_b32_e64 v234, v214, v234, s[48:49]
	v_cndmask_b32_e64 v235, v215, v235, s[48:49]
	v_cndmask_b32_e64 v236, v216, v236, s[48:49]
	v_cndmask_b32_e64 v237, v217, v237, s[48:49]
	v_mov_b32_dpp v214, v32 row_ror:1 row_mask:0xf bank_mask:0xf
	v_mov_b32_dpp v215, v33 row_ror:1 row_mask:0xf bank_mask:0xf
	v_mov_b32_dpp v216, v34 row_ror:1 row_mask:0xf bank_mask:0xf
	v_mov_b32_dpp v217, v35 row_ror:1 row_mask:0xf bank_mask:0xf
	s_nop 1
	v_cndmask_b32_e64 v250, v214, v250, s[48:49]
	v_cndmask_b32_e64 v251, v215, v251, s[48:49]
	v_cndmask_b32_e64 v252, v216, v252, s[48:49]
	v_cndmask_b32_e64 v253, v217, v253, s[48:49]
	v_pk_fma_f32 v[206:207], v[102:103], v[234:235], v[98:99]
	v_pk_fma_f32 v[210:211], v[92:93], v[250:251], v[84:85]
	v_pk_fma_f32 v[208:209], v[104:105], v[236:237], v[100:101]
	v_pk_fma_f32 v[212:213], v[94:95], v[252:253], v[86:87]
	v_pk_fma_f32 v[206:207], v[106:107], v[164:165], v[206:207]
	v_pk_fma_f32 v[210:211], v[88:89], v[168:169], v[210:211]
	v_pk_fma_f32 v[208:209], v[108:109], v[166:167], v[208:209]
	v_pk_fma_f32 v[212:213], v[90:91], v[170:171], v[212:213]
	v_pk_fma_f32 v[206:207], v[110:111], v[60:61], v[206:207]
	v_pk_fma_f32 v[210:211], v[80:81], v[56:57], v[210:211]
	v_pk_fma_f32 v[208:209], v[112:113], v[62:63], v[208:209]
	v_pk_fma_f32 v[212:213], v[82:83], v[58:59], v[212:213]
	v_fma_f32 v214, |v206|, s6, 1.0
	v_fma_f32 v215, |v207|, s6, 1.0
	v_pk_mul_f32 v[218:219], v[206:207], v[206:207]
	s_nop 0
	v_pk_mul_f32 v[218:219], v[218:219], s[36:37] op_sel_hi:[1,0]
	v_rcp_f32_e32 v214, v214
	v_rcp_f32_e32 v215, v215
	v_exp_f32_e32 v218, v218
	v_exp_f32_e32 v219, v219
	v_pk_fma_f32 v[216:217], v[214:215], s[24:25], v[186:187] op_sel_hi:[1,0,0]
	v_max_f32_e32 v220, 0, v206
	v_pk_fma_f32 v[216:217], v[214:215], v[216:217], s[28:29] op_sel_hi:[1,1,0]
	v_max_f32_e32 v221, 0, v207
	v_pk_fma_f32 v[216:217], v[214:215], v[216:217], s[30:31] op_sel_hi:[1,1,0]
	s_nop 0
	v_pk_fma_f32 v[216:217], v[214:215], v[216:217], s[34:35] op_sel_hi:[1,1,0]
	s_nop 0
	v_pk_mul_f32 v[216:217], v[214:215], v[216:217]
	s_nop 0
	v_pk_mul_f32 v[216:217], v[218:219], v[216:217]
	s_nop 0
	v_fma_f32 v206, -|v206|, v216, v220
	v_fma_f32 v207, -|v207|, v217, v221
	v_mul_f32_e32 v206, v210, v206
	v_mul_f32_e32 v207, v211, v207
	v_fma_f32 v214, |v208|, s6, 1.0
	v_fma_f32 v215, |v209|, s6, 1.0
	v_pk_mul_f32 v[218:219], v[208:209], v[208:209]
	s_nop 0
	v_pk_mul_f32 v[218:219], v[218:219], s[36:37] op_sel_hi:[1,0]
	v_rcp_f32_e32 v214, v214
	v_rcp_f32_e32 v215, v215
	v_exp_f32_e32 v218, v218
	v_exp_f32_e32 v219, v219
	v_pk_fma_f32 v[216:217], v[214:215], s[24:25], v[186:187] op_sel_hi:[1,0,0]
	v_max_f32_e32 v220, 0, v208
	v_pk_fma_f32 v[216:217], v[214:215], v[216:217], s[28:29] op_sel_hi:[1,1,0]
	v_max_f32_e32 v221, 0, v209
	v_pk_fma_f32 v[216:217], v[214:215], v[216:217], s[30:31] op_sel_hi:[1,1,0]
	s_nop 0
	v_pk_fma_f32 v[216:217], v[214:215], v[216:217], s[34:35] op_sel_hi:[1,1,0]
	s_nop 0
	v_pk_mul_f32 v[216:217], v[214:215], v[216:217]
	s_nop 0
	v_pk_mul_f32 v[216:217], v[218:219], v[216:217]
	s_nop 0
	v_fma_f32 v208, -|v208|, v216, v220
	v_fma_f32 v209, -|v209|, v217, v221
	v_mul_f32_e32 v208, v212, v208
	v_mul_f32_e32 v209, v213, v209
	v_mov_b64_e32 v[218:219], v[190:191]
	v_cvt_pk_bf16_f32 v220, v206, v207
	v_cvt_pk_bf16_f32 v221, v208, v209
	v_lshl_add_u64 v[126:127], s[56:57], 0, v[184:185]
	s_andn2_b64 exec, exec, s[74:75]
	global_store_dwordx4 v[126:127], v[218:221], off
	s_mov_b64 exec, -1
	s_and_saveexec_b64 s[22:23], s[74:75]
	s_cbranch_execz .Lmy_p5_8
	s_lshr_b32 s18, s16, 6
	s_add_i32 s18, s18, 0
	s_mul_i32 s18, s18, 0x5800
	s_mov_b32 s19, 0
	v_lshlrev_b64 v[214:215], 2, v[182:183]
	v_lshl_add_u64 v[214:215], s[18:19], 0, v[214:215]
	v_lshl_add_u64 v[214:215], s[92:93], 0, v[214:215]
	global_store_dwordx4 v[214:215], v[60:63], off offset:16
	v_lshl_add_u64 v[216:217], v[214:215], 0, s[52:53]
	global_store_dwordx4 v[216:217], v[56:59], off offset:3088
; __device__ __forceinline__ f32x2 gelu_pk(f32x2 v) {
;     const f32x2 av = __builtin_elementwise_abs(v), d = av * 0.2316418882f + 1.0f;
;     f32x2 t; t.x = __builtin_amdgcn_rcpf(d.x); t.y = __builtin_amdgcn_rcpf(d.y);
;     f32x2 q = t * 0.5307027145f + (-0.7265760135f); q = q * t + 0.7107068705f; q = q * t + (-0.142248368f); q = q * t + 0.127414796f; q = q * t;
;     const f32x2 s = (v * v) * (-0.72134752044f);
;     f32x2 e; e.x = __builtin_amdgcn_exp2f(s.x); e.y = __builtin_amdgcn_exp2f(s.y);
;     const f32x2 m = v * (q * e), r = v - m;
;     f32x2 o; o.x = v.x < 0.f ? m.x : r.x; o.y = v.y < 0.f ? m.y : r.y; return o;
;     __device__ __forceinline__ void operator()(AccT& acc, const Unit& u, int wr, int wc, int fr, int fq) const {
;     ...
;                 for (int m = 0; m < 4; ++m) {
;                     const int rl = ai * 128 + wr * 64 + m * 16 + fr;
;                     const f32x4 cg_ = acc[ai][0][m][n], cv_ = acc[ai][1][m][n];
;                     f32x4 p1g, p2g, p1v, p2v;
; #pragma unroll
;                     for (int j = 0; j < 4; ++j) {
;                         p1g[j] = ror1(fr == 15 ? hg[j] : cg_[j]); p2g[j] = ror2(fr >= 14 ? hg[j] : cg_[j]);
;                         p1v[j] = ror1(fr == 15 ? hv[j] : cv_[j]); p2v[j] = ror2(fr >= 14 ? hv[j] : cv_[j]);
;                     }
;                     const f32x4 hcg = bg + w0g * p2g + w1g * p1g + w2g * cg_;
;                     const f32x4 hcv = bv + w0v * p2v + w1v * p1v + w2v * cv_;
;                     const f32x2 ga = gelu_pk((f32x2){hcg[0], hcg[1]}), gb2 = gelu_pk((f32x2){hcg[2], hcg[3]});
;                     u32x2 w; w.x = cvt_pk_bf16(ga.x * hcv[0], ga.y * hcv[1]); w.y = cvt_pk_bf16(gb2.x * hcv[2], gb2.y * hcv[3]);
;                     const int t = tstart + rl;
;                     if (n == 0) stash[ai][m] = w;
;                     else if (rl >= 2) *(u32x4*)(U + (size_t)(arow0 + rl) * FF + colg0) = (u32x4){stash[ai][m].x, stash[ai][m].y, w.x, w.y};
;                     if (rl < 2 || rl >= 254) { float* hp = halo + ((size_t)u.pm * 4 + (rl < 2 ? rl : rl - 252)) * FF2; *(f32x4*)(hp + colg) = cg_; *(f32x4*)(hp + colv) = cv_; }
;                     if (t >= SEQ - 2) { float* cp = conv_p + (size_t)(b * 2 + (t - (SEQ - 2))) * FF2; *(f32x4*)(cp + colg) = cg_; *(f32x4*)(cp + colv) = cv_; }
.Lmy_p5_8:
	s_or_b64 exec, exec, s[22:23]
	v_pk_fma_f32 v[206:207], v[102:103], v[164:165], v[98:99]
	v_pk_fma_f32 v[210:211], v[92:93], v[168:169], v[84:85]
	v_pk_fma_f32 v[208:209], v[104:105], v[166:167], v[100:101]
	v_pk_fma_f32 v[212:213], v[94:95], v[170:171], v[86:87]
	v_pk_fma_f32 v[206:207], v[106:107], v[60:61], v[206:207]
	v_pk_fma_f32 v[210:211], v[88:89], v[56:57], v[210:211]
	v_pk_fma_f32 v[208:209], v[108:109], v[62:63], v[208:209]
	v_pk_fma_f32 v[212:213], v[90:91], v[58:59], v[212:213]
	v_pk_fma_f32 v[206:207], v[110:111], v[52:53], v[206:207]
	v_pk_fma_f32 v[210:211], v[80:81], v[40:41], v[210:211]
	v_pk_fma_f32 v[208:209], v[112:113], v[54:55], v[208:209]
	v_pk_fma_f32 v[212:213], v[82:83], v[42:43], v[212:213]
	v_fma_f32 v214, |v206|, s6, 1.0
	v_fma_f32 v215, |v207|, s6, 1.0
	v_pk_mul_f32 v[218:219], v[206:207], v[206:207]
	s_nop 0
	v_pk_mul_f32 v[218:219], v[218:219], s[36:37] op_sel_hi:[1,0]
	v_rcp_f32_e32 v214, v214
	v_rcp_f32_e32 v215, v215
	v_exp_f32_e32 v218, v218
	v_exp_f32_e32 v219, v219
	v_pk_fma_f32 v[216:217], v[214:215], s[24:25], v[186:187] op_sel_hi:[1,0,0]
	v_max_f32_e32 v220, 0, v206
	v_pk_fma_f32 v[216:217], v[214:215], v[216:217], s[28:29] op_sel_hi:[1,1,0]
	v_max_f32_e32 v221, 0, v207
	v_pk_fma_f32 v[216:217], v[214:215], v[216:217], s[30:31] op_sel_hi:[1,1,0]
	s_nop 0
	v_pk_fma_f32 v[216:217], v[214:215], v[216:217], s[34:35] op_sel_hi:[1,1,0]
	s_nop 0
	v_pk_mul_f32 v[216:217], v[214:215], v[216:217]
	s_nop 0
	v_pk_mul_f32 v[216:217], v[218:219], v[216:217]
	s_nop 0
	v_fma_f32 v206, -|v206|, v216, v220
	v_fma_f32 v207, -|v207|, v217, v221
	v_mul_f32_e32 v206, v210, v206
	v_mul_f32_e32 v207, v211, v207
	v_fma_f32 v214, |v208|, s6, 1.0
	v_fma_f32 v215, |v209|, s6, 1.0
	v_pk_mul_f32 v[218:219], v[208:209], v[208:209]
	s_nop 0
	v_pk_mul_f32 v[218:219], v[218:219], s[36:37] op_sel_hi:[1,0]
	v_rcp_f32_e32 v214, v214
	v_rcp_f32_e32 v215, v215
	v_exp_f32_e32 v218, v218
	v_exp_f32_e32 v219, v219
	v_pk_fma_f32 v[216:217], v[214:215], s[24:25], v[186:187] op_sel_hi:[1,0,0]
	v_max_f32_e32 v220, 0, v208
	v_pk_fma_f32 v[216:217], v[214:215], v[216:217], s[28:29] op_sel_hi:[1,1,0]
	v_max_f32_e32 v221, 0, v209
	v_pk_fma_f32 v[216:217], v[214:215], v[216:217], s[30:31] op_sel_hi:[1,1,0]
	s_nop 0
	v_pk_fma_f32 v[216:217], v[214:215], v[216:217], s[34:35] op_sel_hi:[1,1,0]
	s_nop 0
	v_pk_mul_f32 v[216:217], v[214:215], v[216:217]
	s_nop 0
	v_pk_mul_f32 v[216:217], v[218:219], v[216:217]
	s_nop 0
	v_fma_f32 v208, -|v208|, v216, v220
	v_fma_f32 v209, -|v209|, v217, v221
	v_mul_f32_e32 v208, v212, v208
	v_mul_f32_e32 v209, v213, v209
	v_mov_b64_e32 v[218:219], v[238:239]
	v_cvt_pk_bf16_f32 v220, v206, v207
	v_cvt_pk_bf16_f32 v221, v208, v209
	v_lshl_add_u64 v[126:127], s[58:59], 0, v[184:185]
	s_andn2_b64 exec, exec, s[74:75]
	global_store_dwordx4 v[126:127], v[218:221], off
	s_mov_b64 exec, -1
	s_and_saveexec_b64 s[22:23], s[74:75]
	s_cbranch_execz .Lmy_p5_9
	s_lshr_b32 s18, s16, 6
	s_add_i32 s18, s18, 1
	s_mul_i32 s18, s18, 0x5800
	s_mov_b32 s19, 0
	v_lshlrev_b64 v[214:215], 2, v[182:183]
	v_lshl_add_u64 v[214:215], s[18:19], 0, v[214:215]
	v_lshl_add_u64 v[214:215], s[92:93], 0, v[214:215]
	global_store_dwordx4 v[214:215], v[52:55], off offset:16
	v_lshl_add_u64 v[216:217], v[214:215], 0, s[52:53]
	global_store_dwordx4 v[216:217], v[40:43], off offset:3088
.Lmy_p5_9:
	s_or_b64 exec, exec, s[22:23]
	v_pk_fma_f32 v[206:207], v[102:103], v[60:61], v[98:99]
	v_pk_fma_f32 v[210:211], v[92:93], v[56:57], v[84:85]
	v_pk_fma_f32 v[208:209], v[104:105], v[62:63], v[100:101]
	v_pk_fma_f32 v[212:213], v[94:95], v[58:59], v[86:87]
	v_pk_fma_f32 v[206:207], v[106:107], v[52:53], v[206:207]
	v_pk_fma_f32 v[210:211], v[88:89], v[40:41], v[210:211]
	v_pk_fma_f32 v[208:209], v[108:109], v[54:55], v[208:209]
	v_pk_fma_f32 v[212:213], v[90:91], v[42:43], v[212:213]
	v_pk_fma_f32 v[206:207], v[110:111], v[36:37], v[206:207]
	v_pk_fma_f32 v[210:211], v[80:81], v[32:33], v[210:211]
	v_pk_fma_f32 v[208:209], v[112:113], v[38:39], v[208:209]
	v_pk_fma_f32 v[212:213], v[82:83], v[34:35], v[212:213]
	v_fma_f32 v214, |v206|, s6, 1.0
	v_fma_f32 v215, |v207|, s6, 1.0
	v_pk_mul_f32 v[218:219], v[206:207], v[206:207]
	s_nop 0
	v_pk_mul_f32 v[218:219], v[218:219], s[36:37] op_sel_hi:[1,0]
	v_rcp_f32_e32 v214, v214
	v_rcp_f32_e32 v215, v215
	v_exp_f32_e32 v218, v218
	v_exp_f32_e32 v219, v219
	v_pk_fma_f32 v[216:217], v[214:215], s[24:25], v[186:187] op_sel_hi:[1,0,0]
	v_max_f32_e32 v220, 0, v206
	v_pk_fma_f32 v[216:217], v[214:215], v[216:217], s[28:29] op_sel_hi:[1,1,0]
	v_max_f32_e32 v221, 0, v207
	v_pk_fma_f32 v[216:217], v[214:215], v[216:217], s[30:31] op_sel_hi:[1,1,0]
	s_nop 0
	v_pk_fma_f32 v[216:217], v[214:215], v[216:217], s[34:35] op_sel_hi:[1,1,0]
	s_nop 0
	v_pk_mul_f32 v[216:217], v[214:215], v[216:217]
	s_nop 0
	v_pk_mul_f32 v[216:217], v[218:219], v[216:217]
	s_nop 0
	v_fma_f32 v206, -|v206|, v216, v220
	v_fma_f32 v207, -|v207|, v217, v221
	v_mul_f32_e32 v206, v210, v206
	v_mul_f32_e32 v207, v211, v207
	v_fma_f32 v214, |v208|, s6, 1.0
	v_fma_f32 v215, |v209|, s6, 1.0
	v_pk_mul_f32 v[218:219], v[208:209], v[208:209]
	s_nop 0
	v_pk_mul_f32 v[218:219], v[218:219], s[36:37] op_sel_hi:[1,0]
	v_rcp_f32_e32 v214, v214
	v_rcp_f32_e32 v215, v215
	v_exp_f32_e32 v218, v218
	v_exp_f32_e32 v219, v219
	v_pk_fma_f32 v[216:217], v[214:215], s[24:25], v[186:187] op_sel_hi:[1,0,0]
	v_max_f32_e32 v220, 0, v208
	v_pk_fma_f32 v[216:217], v[214:215], v[216:217], s[28:29] op_sel_hi:[1,1,0]
	v_max_f32_e32 v221, 0, v209
	v_pk_fma_f32 v[216:217], v[214:215], v[216:217], s[30:31] op_sel_hi:[1,1,0]
	s_nop 0
	v_pk_fma_f32 v[216:217], v[214:215], v[216:217], s[34:35] op_sel_hi:[1,1,0]
; __device__ __forceinline__ f32x2 gelu_pk(f32x2 v) {
;     const f32x2 av = __builtin_elementwise_abs(v), d = av * 0.2316418882f + 1.0f;
;     f32x2 t; t.x = __builtin_amdgcn_rcpf(d.x); t.y = __builtin_amdgcn_rcpf(d.y);
;     __device__ __forceinline__ void operator()(AccT& acc, const Unit& u, int wr, int wc, int fr, int fq) const {
;     ...
;             for (int ai = 0; ai < 2; ++ai) {
;                 f32x4 hg = (f32x4){0.f, 0.f, 0.f, 0.f}, hv = hg;
;                 const int s = ai * 2 + wr;
;                 if (s > 0 && fr >= 14) {
;                     hg = *(const LAS f32x4*)(xch + (((s - 1) * 2 + (fr - 14)) * 256 + wc * 32 + fq * 8 + n * 4));
;                     hv = *(const LAS f32x4*)(xch + (((s - 1) * 2 + (fr - 14)) * 256 + 128 + wc * 32 + fq * 8 + n * 4));
;                 }
; #pragma unroll
;                 for (int m = 0; m < 4; ++m) {
;                     const int rl = ai * 128 + wr * 64 + m * 16 + fr;
;                     const f32x4 cg_ = acc[ai][0][m][n], cv_ = acc[ai][1][m][n];
;                     f32x4 p1g, p2g, p1v, p2v;
; #pragma unroll
;                     for (int j = 0; j < 4; ++j) {
;                         p1g[j] = ror1(fr == 15 ? hg[j] : cg_[j]); p2g[j] = ror2(fr >= 14 ? hg[j] : cg_[j]);
;                         p1v[j] = ror1(fr == 15 ? hv[j] : cv_[j]); p2v[j] = ror2(fr >= 14 ? hv[j] : cv_[j]);
;                     }
;                     const f32x4 hcg = bg + w0g * p2g + w1g * p1g + w2g * cg_;
;                     const f32x4 hcv = bv + w0v * p2v + w1v * p1v + w2v * cv_;
;                     const f32x2 ga = gelu_pk((f32x2){hcg[0], hcg[1]}), gb2 = gelu_pk((f32x2){hcg[2], hcg[3]});
;                     u32x2 w; w.x = cvt_pk_bf16(ga.x * hcv[0], ga.y * hcv[1]); w.y = cvt_pk_bf16(gb2.x * hcv[2], gb2.y * hcv[3]);
;                     const int t = tstart + rl;
;                     if (n == 0) stash[ai][m] = w;
;                     else if (rl >= 2) *(u32x4*)(U + (size_t)(arow0 + rl) * FF + colg0) = (u32x4){stash[ai][m].x, stash[ai][m].y, w.x, w.y};
;                     if (rl < 2 || rl >= 254) { float* hp = halo + ((size_t)u.pm * 4 + (rl < 2 ? rl : rl - 252)) * FF2; *(f32x4*)(hp + colg) = cg_; *(f32x4*)(hp + colv) = cv_; }
;                     if (t >= SEQ - 2) { float* cp = conv_p + (size_t)(b * 2 + (t - (SEQ - 2))) * FF2; *(f32x4*)(cp + colg) = cg_; *(f32x4*)(cp + colv) = cv_; }
	s_nop 0
	v_pk_mul_f32 v[216:217], v[214:215], v[216:217]
	s_nop 0
	v_pk_mul_f32 v[216:217], v[218:219], v[216:217]
	s_nop 0
	v_fma_f32 v208, -|v208|, v216, v220
	v_fma_f32 v209, -|v209|, v217, v221
	v_mul_f32_e32 v208, v212, v208
	v_mul_f32_e32 v209, v213, v209
	v_mov_b64_e32 v[218:219], v[160:161]
	v_cvt_pk_bf16_f32 v220, v206, v207
	v_cvt_pk_bf16_f32 v221, v208, v209
	v_lshl_add_u64 v[126:127], s[60:61], 0, v[184:185]
	global_store_dwordx4 v[126:127], v[218:221], off
	v_pk_fma_f32 v[206:207], v[102:103], v[52:53], v[98:99]
	v_pk_fma_f32 v[210:211], v[92:93], v[40:41], v[84:85]
	v_pk_fma_f32 v[208:209], v[104:105], v[54:55], v[100:101]
	v_pk_fma_f32 v[212:213], v[94:95], v[42:43], v[86:87]
	v_pk_fma_f32 v[206:207], v[106:107], v[36:37], v[206:207]
	v_pk_fma_f32 v[210:211], v[88:89], v[32:33], v[210:211]
	v_pk_fma_f32 v[208:209], v[108:109], v[38:39], v[208:209]
	v_pk_fma_f32 v[212:213], v[90:91], v[34:35], v[212:213]
	v_pk_fma_f32 v[206:207], v[110:111], v[48:49], v[206:207]
	v_pk_fma_f32 v[210:211], v[80:81], v[44:45], v[210:211]
	v_pk_fma_f32 v[208:209], v[112:113], v[50:51], v[208:209]
	v_pk_fma_f32 v[212:213], v[82:83], v[46:47], v[212:213]
	v_fma_f32 v214, |v206|, s6, 1.0
	v_fma_f32 v215, |v207|, s6, 1.0
	v_pk_mul_f32 v[218:219], v[206:207], v[206:207]
	s_nop 0
	v_pk_mul_f32 v[218:219], v[218:219], s[36:37] op_sel_hi:[1,0]
	v_rcp_f32_e32 v214, v214
	v_rcp_f32_e32 v215, v215
	v_exp_f32_e32 v218, v218
	v_exp_f32_e32 v219, v219
	v_pk_fma_f32 v[216:217], v[214:215], s[24:25], v[186:187] op_sel_hi:[1,0,0]
	v_max_f32_e32 v220, 0, v206
	v_pk_fma_f32 v[216:217], v[214:215], v[216:217], s[28:29] op_sel_hi:[1,1,0]
	v_max_f32_e32 v221, 0, v207
	v_pk_fma_f32 v[216:217], v[214:215], v[216:217], s[30:31] op_sel_hi:[1,1,0]
	s_nop 0
	v_pk_fma_f32 v[216:217], v[214:215], v[216:217], s[34:35] op_sel_hi:[1,1,0]
	s_nop 0
	v_pk_mul_f32 v[216:217], v[214:215], v[216:217]
	s_nop 0
	v_pk_mul_f32 v[216:217], v[218:219], v[216:217]
	s_nop 0
	v_fma_f32 v206, -|v206|, v216, v220
	v_fma_f32 v207, -|v207|, v217, v221
	v_mul_f32_e32 v206, v210, v206
	v_mul_f32_e32 v207, v211, v207
	v_fma_f32 v214, |v208|, s6, 1.0
	v_fma_f32 v215, |v209|, s6, 1.0
	v_pk_mul_f32 v[218:219], v[208:209], v[208:209]
	s_nop 0
	v_pk_mul_f32 v[218:219], v[218:219], s[36:37] op_sel_hi:[1,0]
	v_rcp_f32_e32 v214, v214
	v_rcp_f32_e32 v215, v215
	v_exp_f32_e32 v218, v218
	v_exp_f32_e32 v219, v219
	v_pk_fma_f32 v[216:217], v[214:215], s[24:25], v[186:187] op_sel_hi:[1,0,0]
	v_max_f32_e32 v220, 0, v208
	v_pk_fma_f32 v[216:217], v[214:215], v[216:217], s[28:29] op_sel_hi:[1,1,0]
	v_max_f32_e32 v221, 0, v209
	v_pk_fma_f32 v[216:217], v[214:215], v[216:217], s[30:31] op_sel_hi:[1,1,0]
	s_nop 0
	v_pk_fma_f32 v[216:217], v[214:215], v[216:217], s[34:35] op_sel_hi:[1,1,0]
	s_nop 0
	v_pk_mul_f32 v[216:217], v[214:215], v[216:217]
	s_nop 0
	v_pk_mul_f32 v[216:217], v[218:219], v[216:217]
	s_nop 0
	v_fma_f32 v208, -|v208|, v216, v220
	v_fma_f32 v209, -|v209|, v217, v221
	v_mul_f32_e32 v208, v212, v208
	v_mul_f32_e32 v209, v213, v209
	v_mov_b64_e32 v[218:219], v[144:145]
	v_cvt_pk_bf16_f32 v220, v206, v207
	v_cvt_pk_bf16_f32 v221, v208, v209
	v_lshl_add_u64 v[126:127], s[62:63], 0, v[184:185]
	global_store_dwordx4 v[126:127], v[218:221], off
	v_mov_b64_e32 v[164:165], 0
	v_mov_b64_e32 v[166:167], 0
	v_mov_b64_e32 v[168:169], 0
	v_mov_b64_e32 v[170:171], 0
	v_mov_b64_e32 v[234:235], 0
	v_mov_b64_e32 v[236:237], 0
	v_mov_b64_e32 v[250:251], 0
	v_mov_b64_e32 v[252:253], 0
	s_and_saveexec_b64 s[20:21], s[48:49]
	s_cbranch_execz .Lmy_p5_10
	ds_read_b128 v[234:237], v188 offset:4128
	ds_read_b128 v[250:253], v188 offset:4144
	ds_read_b128 v[164:167], v188 offset:4192
	ds_read_b128 v[168:171], v188 offset:4208
.Lmy_p5_10:
	s_or_b64 exec, exec, s[20:21]
	s_waitcnt lgkmcnt(0)
	s_nop 4
	v_mov_b32_dpp v214, v16 row_ror:1 row_mask:0xf bank_mask:0xf
	v_mov_b32_dpp v215, v17 row_ror:1 row_mask:0xf bank_mask:0xf
	v_mov_b32_dpp v216, v18 row_ror:1 row_mask:0xf bank_mask:0xf
	v_mov_b32_dpp v217, v19 row_ror:1 row_mask:0xf bank_mask:0xf
	s_nop 1
	v_cndmask_b32_e64 v164, v214, v164, s[48:49]
	v_cndmask_b32_e64 v165, v215, v165, s[48:49]
	v_cndmask_b32_e64 v166, v216, v166, s[48:49]
	v_cndmask_b32_e64 v167, v217, v167, s[48:49]
	v_mov_b32_dpp v214, v20 row_ror:1 row_mask:0xf bank_mask:0xf
	v_mov_b32_dpp v215, v21 row_ror:1 row_mask:0xf bank_mask:0xf
	v_mov_b32_dpp v216, v22 row_ror:1 row_mask:0xf bank_mask:0xf
	v_mov_b32_dpp v217, v23 row_ror:1 row_mask:0xf bank_mask:0xf
	s_nop 1
	v_cndmask_b32_e64 v168, v214, v168, s[48:49]
	v_cndmask_b32_e64 v169, v215, v169, s[48:49]
	v_cndmask_b32_e64 v170, v216, v170, s[48:49]
	v_cndmask_b32_e64 v171, v217, v171, s[48:49]
	v_mov_b32_dpp v214, v4 row_ror:1 row_mask:0xf bank_mask:0xf
	v_mov_b32_dpp v215, v5 row_ror:1 row_mask:0xf bank_mask:0xf
	v_mov_b32_dpp v216, v6 row_ror:1 row_mask:0xf bank_mask:0xf
	v_mov_b32_dpp v217, v7 row_ror:1 row_mask:0xf bank_mask:0xf
	s_nop 1
	v_cndmask_b32_e64 v234, v214, v234, s[48:49]
	v_cndmask_b32_e64 v235, v215, v235, s[48:49]
	v_cndmask_b32_e64 v236, v216, v236, s[48:49]
	v_cndmask_b32_e64 v237, v217, v237, s[48:49]
	v_mov_b32_dpp v214, v0 row_ror:1 row_mask:0xf bank_mask:0xf
	v_mov_b32_dpp v215, v1 row_ror:1 row_mask:0xf bank_mask:0xf
	v_mov_b32_dpp v216, v2 row_ror:1 row_mask:0xf bank_mask:0xf
	v_mov_b32_dpp v217, v3 row_ror:1 row_mask:0xf bank_mask:0xf
	s_nop 1
	v_cndmask_b32_e64 v250, v214, v250, s[48:49]
	v_cndmask_b32_e64 v251, v215, v251, s[48:49]
	v_cndmask_b32_e64 v252, v216, v252, s[48:49]
	v_cndmask_b32_e64 v253, v217, v253, s[48:49]
	v_pk_fma_f32 v[206:207], v[102:103], v[234:235], v[98:99]
	v_pk_fma_f32 v[210:211], v[92:93], v[250:251], v[84:85]
; __device__ __forceinline__ unsigned cvt_pk_bf16(float lo, float hi) { unsigned r; asm volatile("v_cvt_pk_bf16_f32 %0, %1, %2" : "=v"(r) : "v"(lo), "v"(hi)); return r; }
; __device__ __forceinline__ float ror1(float x) { return __builtin_bit_cast(float, __builtin_amdgcn_update_dpp(0, __builtin_bit_cast(int, x), 0x121, 0xf, 0xf, false)); }
; __device__ __forceinline__ f32x2 gelu_pk(f32x2 v) {
;     const f32x2 av = __builtin_elementwise_abs(v), d = av * 0.2316418882f + 1.0f;
;     f32x2 t; t.x = __builtin_amdgcn_rcpf(d.x); t.y = __builtin_amdgcn_rcpf(d.y);
;     f32x2 q = t * 0.5307027145f + (-0.7265760135f); q = q * t + 0.7107068705f; q = q * t + (-0.142248368f); q = q * t + 0.127414796f; q = q * t;
;     const f32x2 s = (v * v) * (-0.72134752044f);
;     f32x2 e; e.x = __builtin_amdgcn_exp2f(s.x); e.y = __builtin_amdgcn_exp2f(s.y);
;     const f32x2 m = v * (q * e), r = v - m;
;     f32x2 o; o.x = v.x < 0.f ? m.x : r.x; o.y = v.y < 0.f ? m.y : r.y; return o;
;     __device__ __forceinline__ void operator()(AccT& acc, const Unit& u, int wr, int wc, int fr, int fq) const {
;     ...
;                 for (int m = 0; m < 4; ++m) {
;                     const int rl = ai * 128 + wr * 64 + m * 16 + fr;
;                     const f32x4 cg_ = acc[ai][0][m][n], cv_ = acc[ai][1][m][n];
;                     f32x4 p1g, p2g, p1v, p2v;
; #pragma unroll
;                     for (int j = 0; j < 4; ++j) {
;                         p1g[j] = ror1(fr == 15 ? hg[j] : cg_[j]); p2g[j] = ror2(fr >= 14 ? hg[j] : cg_[j]);
;                         p1v[j] = ror1(fr == 15 ? hv[j] : cv_[j]); p2v[j] = ror2(fr >= 14 ? hv[j] : cv_[j]);
;                     }
;                     const f32x4 hcg = bg + w0g * p2g + w1g * p1g + w2g * cg_;
;                     const f32x4 hcv = bv + w0v * p2v + w1v * p1v + w2v * cv_;
;                     const f32x2 ga = gelu_pk((f32x2){hcg[0], hcg[1]}), gb2 = gelu_pk((f32x2){hcg[2], hcg[3]});
;                     u32x2 w; w.x = cvt_pk_bf16(ga.x * hcv[0], ga.y * hcv[1]); w.y = cvt_pk_bf16(gb2.x * hcv[2], gb2.y * hcv[3]);
;                     const int t = tstart + rl;
;                     if (n == 0) stash[ai][m] = w;
;                     else if (rl >= 2) *(u32x4*)(U + (size_t)(arow0 + rl) * FF + colg0) = (u32x4){stash[ai][m].x, stash[ai][m].y, w.x, w.y};
	v_pk_fma_f32 v[208:209], v[104:105], v[236:237], v[100:101]
	v_pk_fma_f32 v[212:213], v[94:95], v[252:253], v[86:87]
	v_pk_fma_f32 v[206:207], v[106:107], v[164:165], v[206:207]
	v_pk_fma_f32 v[210:211], v[88:89], v[168:169], v[210:211]
	v_pk_fma_f32 v[208:209], v[108:109], v[166:167], v[208:209]
	v_pk_fma_f32 v[212:213], v[90:91], v[170:171], v[212:213]
	v_pk_fma_f32 v[206:207], v[110:111], v[28:29], v[206:207]
	v_pk_fma_f32 v[210:211], v[80:81], v[24:25], v[210:211]
	v_pk_fma_f32 v[208:209], v[112:113], v[30:31], v[208:209]
	v_pk_fma_f32 v[212:213], v[82:83], v[26:27], v[212:213]
	v_fma_f32 v214, |v206|, s6, 1.0
	v_fma_f32 v215, |v207|, s6, 1.0
	v_pk_mul_f32 v[218:219], v[206:207], v[206:207]
	s_nop 0
	v_pk_mul_f32 v[218:219], v[218:219], s[36:37] op_sel_hi:[1,0]
	v_rcp_f32_e32 v214, v214
	v_rcp_f32_e32 v215, v215
	v_exp_f32_e32 v218, v218
	v_exp_f32_e32 v219, v219
	v_pk_fma_f32 v[216:217], v[214:215], s[24:25], v[186:187] op_sel_hi:[1,0,0]
	v_max_f32_e32 v220, 0, v206
	v_pk_fma_f32 v[216:217], v[214:215], v[216:217], s[28:29] op_sel_hi:[1,1,0]
	v_max_f32_e32 v221, 0, v207
	v_pk_fma_f32 v[216:217], v[214:215], v[216:217], s[30:31] op_sel_hi:[1,1,0]
	s_nop 0
	v_pk_fma_f32 v[216:217], v[214:215], v[216:217], s[34:35] op_sel_hi:[1,1,0]
	s_nop 0
	v_pk_mul_f32 v[216:217], v[214:215], v[216:217]
	s_nop 0
	v_pk_mul_f32 v[216:217], v[218:219], v[216:217]
	s_nop 0
	v_fma_f32 v206, -|v206|, v216, v220
	v_fma_f32 v207, -|v207|, v217, v221
	v_mul_f32_e32 v206, v210, v206
	v_mul_f32_e32 v207, v211, v207
	v_fma_f32 v214, |v208|, s6, 1.0
	v_fma_f32 v215, |v209|, s6, 1.0
	v_pk_mul_f32 v[218:219], v[208:209], v[208:209]
	s_nop 0
	v_pk_mul_f32 v[218:219], v[218:219], s[36:37] op_sel_hi:[1,0]
	v_rcp_f32_e32 v214, v214
	v_rcp_f32_e32 v215, v215
	v_exp_f32_e32 v218, v218
	v_exp_f32_e32 v219, v219
	v_pk_fma_f32 v[216:217], v[214:215], s[24:25], v[186:187] op_sel_hi:[1,0,0]
	v_max_f32_e32 v220, 0, v208
	v_pk_fma_f32 v[216:217], v[214:215], v[216:217], s[28:29] op_sel_hi:[1,1,0]
	v_max_f32_e32 v221, 0, v209
	v_pk_fma_f32 v[216:217], v[214:215], v[216:217], s[30:31] op_sel_hi:[1,1,0]
	s_nop 0
	v_pk_fma_f32 v[216:217], v[214:215], v[216:217], s[34:35] op_sel_hi:[1,1,0]
	s_nop 0
	v_pk_mul_f32 v[216:217], v[214:215], v[216:217]
	s_nop 0
	v_pk_mul_f32 v[216:217], v[218:219], v[216:217]
	s_nop 0
	v_fma_f32 v208, -|v208|, v216, v220
	v_fma_f32 v209, -|v209|, v217, v221
	v_mul_f32_e32 v208, v212, v208
	v_mul_f32_e32 v209, v213, v209
	v_mov_b64_e32 v[218:219], v[156:157]
	v_cvt_pk_bf16_f32 v220, v206, v207
	v_cvt_pk_bf16_f32 v221, v208, v209
	v_lshl_add_u64 v[126:127], s[64:65], 0, v[184:185]
	global_store_dwordx4 v[126:127], v[218:221], off
	v_pk_fma_f32 v[206:207], v[102:103], v[164:165], v[98:99]
	v_pk_fma_f32 v[210:211], v[92:93], v[168:169], v[84:85]
	v_pk_fma_f32 v[208:209], v[104:105], v[166:167], v[100:101]
	v_pk_fma_f32 v[212:213], v[94:95], v[170:171], v[86:87]
	v_pk_fma_f32 v[206:207], v[106:107], v[28:29], v[206:207]
	v_pk_fma_f32 v[210:211], v[88:89], v[24:25], v[210:211]
	v_pk_fma_f32 v[208:209], v[108:109], v[30:31], v[208:209]
	v_pk_fma_f32 v[212:213], v[90:91], v[26:27], v[212:213]
	v_pk_fma_f32 v[206:207], v[110:111], v[12:13], v[206:207]
	v_pk_fma_f32 v[210:211], v[80:81], v[8:9], v[210:211]
	v_pk_fma_f32 v[208:209], v[112:113], v[14:15], v[208:209]
	v_pk_fma_f32 v[212:213], v[82:83], v[10:11], v[212:213]
	v_fma_f32 v214, |v206|, s6, 1.0
	v_fma_f32 v215, |v207|, s6, 1.0
	v_pk_mul_f32 v[218:219], v[206:207], v[206:207]
	s_nop 0
	v_pk_mul_f32 v[218:219], v[218:219], s[36:37] op_sel_hi:[1,0]
	v_rcp_f32_e32 v214, v214
	v_rcp_f32_e32 v215, v215
	v_exp_f32_e32 v218, v218
	v_exp_f32_e32 v219, v219
	v_pk_fma_f32 v[216:217], v[214:215], s[24:25], v[186:187] op_sel_hi:[1,0,0]
	v_max_f32_e32 v220, 0, v206
	v_pk_fma_f32 v[216:217], v[214:215], v[216:217], s[28:29] op_sel_hi:[1,1,0]
	v_max_f32_e32 v221, 0, v207
	v_pk_fma_f32 v[216:217], v[214:215], v[216:217], s[30:31] op_sel_hi:[1,1,0]
	s_nop 0
	v_pk_fma_f32 v[216:217], v[214:215], v[216:217], s[34:35] op_sel_hi:[1,1,0]
	s_nop 0
	v_pk_mul_f32 v[216:217], v[214:215], v[216:217]
	s_nop 0
	v_pk_mul_f32 v[216:217], v[218:219], v[216:217]
	s_nop 0
	v_fma_f32 v206, -|v206|, v216, v220
	v_fma_f32 v207, -|v207|, v217, v221
	v_mul_f32_e32 v206, v210, v206
	v_mul_f32_e32 v207, v211, v207
	v_fma_f32 v214, |v208|, s6, 1.0
	v_fma_f32 v215, |v209|, s6, 1.0
	v_pk_mul_f32 v[218:219], v[208:209], v[208:209]
	s_nop 0
	v_pk_mul_f32 v[218:219], v[218:219], s[36:37] op_sel_hi:[1,0]
	v_rcp_f32_e32 v214, v214
	v_rcp_f32_e32 v215, v215
	v_exp_f32_e32 v218, v218
	v_exp_f32_e32 v219, v219
	v_pk_fma_f32 v[216:217], v[214:215], s[24:25], v[186:187] op_sel_hi:[1,0,0]
	v_max_f32_e32 v220, 0, v208
	v_pk_fma_f32 v[216:217], v[214:215], v[216:217], s[28:29] op_sel_hi:[1,1,0]
	v_max_f32_e32 v221, 0, v209
	v_pk_fma_f32 v[216:217], v[214:215], v[216:217], s[30:31] op_sel_hi:[1,1,0]
	s_nop 0
	v_pk_fma_f32 v[216:217], v[214:215], v[216:217], s[34:35] op_sel_hi:[1,1,0]
	s_nop 0
	v_pk_mul_f32 v[216:217], v[214:215], v[216:217]
	s_nop 0
	v_pk_mul_f32 v[216:217], v[218:219], v[216:217]
	s_nop 0
	v_fma_f32 v208, -|v208|, v216, v220
	v_fma_f32 v209, -|v209|, v217, v221
	v_mul_f32_e32 v208, v212, v208
	v_mul_f32_e32 v209, v213, v209
	v_mov_b64_e32 v[218:219], v[118:119]
	v_cvt_pk_bf16_f32 v220, v206, v207
	v_cvt_pk_bf16_f32 v221, v208, v209
	v_lshl_add_u64 v[126:127], s[66:67], 0, v[184:185]
	global_store_dwordx4 v[126:127], v[218:221], off
	v_pk_fma_f32 v[206:207], v[102:103], v[28:29], v[98:99]
	v_pk_fma_f32 v[210:211], v[92:93], v[24:25], v[84:85]
	v_pk_fma_f32 v[208:209], v[104:105], v[30:31], v[100:101]
	v_pk_fma_f32 v[212:213], v[94:95], v[26:27], v[86:87]
; __device__ __forceinline__ unsigned cvt_pk_bf16(float lo, float hi) { unsigned r; asm volatile("v_cvt_pk_bf16_f32 %0, %1, %2" : "=v"(r) : "v"(lo), "v"(hi)); return r; }
; __device__ __forceinline__ float ror1(float x) { return __builtin_bit_cast(float, __builtin_amdgcn_update_dpp(0, __builtin_bit_cast(int, x), 0x121, 0xf, 0xf, false)); }
; __device__ __forceinline__ f32x2 gelu_pk(f32x2 v) {
;     const f32x2 av = __builtin_elementwise_abs(v), d = av * 0.2316418882f + 1.0f;
;     f32x2 t; t.x = __builtin_amdgcn_rcpf(d.x); t.y = __builtin_amdgcn_rcpf(d.y);
;     f32x2 q = t * 0.5307027145f + (-0.7265760135f); q = q * t + 0.7107068705f; q = q * t + (-0.142248368f); q = q * t + 0.127414796f; q = q * t;
;     const f32x2 s = (v * v) * (-0.72134752044f);
;     f32x2 e; e.x = __builtin_amdgcn_exp2f(s.x); e.y = __builtin_amdgcn_exp2f(s.y);
;     const f32x2 m = v * (q * e), r = v - m;
;     f32x2 o; o.x = v.x < 0.f ? m.x : r.x; o.y = v.y < 0.f ? m.y : r.y; return o;
;     __device__ __forceinline__ void operator()(AccT& acc, const Unit& u, int wr, int wc, int fr, int fq) const {
;     ...
;                     for (int j = 0; j < 4; ++j) {
;                         p1g[j] = ror1(fr == 15 ? hg[j] : cg_[j]); p2g[j] = ror2(fr >= 14 ? hg[j] : cg_[j]);
;                         p1v[j] = ror1(fr == 15 ? hv[j] : cv_[j]); p2v[j] = ror2(fr >= 14 ? hv[j] : cv_[j]);
;                     }
;                     const f32x4 hcg = bg + w0g * p2g + w1g * p1g + w2g * cg_;
;                     const f32x4 hcv = bv + w0v * p2v + w1v * p1v + w2v * cv_;
;                     const f32x2 ga = gelu_pk((f32x2){hcg[0], hcg[1]}), gb2 = gelu_pk((f32x2){hcg[2], hcg[3]});
;                     u32x2 w; w.x = cvt_pk_bf16(ga.x * hcv[0], ga.y * hcv[1]); w.y = cvt_pk_bf16(gb2.x * hcv[2], gb2.y * hcv[3]);
;                     const int t = tstart + rl;
;                     if (n == 0) stash[ai][m] = w;
;                     else if (rl >= 2) *(u32x4*)(U + (size_t)(arow0 + rl) * FF + colg0) = (u32x4){stash[ai][m].x, stash[ai][m].y, w.x, w.y};
;                     if (rl < 2 || rl >= 254) { float* hp = halo + ((size_t)u.pm * 4 + (rl < 2 ? rl : rl - 252)) * FF2; *(f32x4*)(hp + colg) = cg_; *(f32x4*)(hp + colv) = cv_; }
;                     if (t >= SEQ - 2) { float* cp = conv_p + (size_t)(b * 2 + (t - (SEQ - 2))) * FF2; *(f32x4*)(cp + colg) = cg_; *(f32x4*)(cp + colv) = cv_; }
	v_pk_fma_f32 v[206:207], v[106:107], v[12:13], v[206:207]
	v_pk_fma_f32 v[210:211], v[88:89], v[8:9], v[210:211]
	v_pk_fma_f32 v[208:209], v[108:109], v[14:15], v[208:209]
	v_pk_fma_f32 v[212:213], v[90:91], v[10:11], v[212:213]
	v_pk_fma_f32 v[206:207], v[110:111], v[4:5], v[206:207]
	v_pk_fma_f32 v[210:211], v[80:81], v[0:1], v[210:211]
	v_pk_fma_f32 v[208:209], v[112:113], v[6:7], v[208:209]
	v_pk_fma_f32 v[212:213], v[82:83], v[2:3], v[212:213]
	v_fma_f32 v214, |v206|, s6, 1.0
	v_fma_f32 v215, |v207|, s6, 1.0
	v_pk_mul_f32 v[218:219], v[206:207], v[206:207]
	s_nop 0
	v_pk_mul_f32 v[218:219], v[218:219], s[36:37] op_sel_hi:[1,0]
	v_rcp_f32_e32 v214, v214
	v_rcp_f32_e32 v215, v215
	v_exp_f32_e32 v218, v218
	v_exp_f32_e32 v219, v219
	v_pk_fma_f32 v[216:217], v[214:215], s[24:25], v[186:187] op_sel_hi:[1,0,0]
	v_max_f32_e32 v220, 0, v206
	v_pk_fma_f32 v[216:217], v[214:215], v[216:217], s[28:29] op_sel_hi:[1,1,0]
	v_max_f32_e32 v221, 0, v207
	v_pk_fma_f32 v[216:217], v[214:215], v[216:217], s[30:31] op_sel_hi:[1,1,0]
	s_nop 0
	v_pk_fma_f32 v[216:217], v[214:215], v[216:217], s[34:35] op_sel_hi:[1,1,0]
	s_nop 0
	v_pk_mul_f32 v[216:217], v[214:215], v[216:217]
	s_nop 0
	v_pk_mul_f32 v[216:217], v[218:219], v[216:217]
	s_nop 0
	v_fma_f32 v206, -|v206|, v216, v220
	v_fma_f32 v207, -|v207|, v217, v221
	v_mul_f32_e32 v206, v210, v206
	v_mul_f32_e32 v207, v211, v207
	v_fma_f32 v214, |v208|, s6, 1.0
	v_fma_f32 v215, |v209|, s6, 1.0
	v_pk_mul_f32 v[218:219], v[208:209], v[208:209]
	s_nop 0
	v_pk_mul_f32 v[218:219], v[218:219], s[36:37] op_sel_hi:[1,0]
	v_rcp_f32_e32 v214, v214
	v_rcp_f32_e32 v215, v215
	v_exp_f32_e32 v218, v218
	v_exp_f32_e32 v219, v219
	v_pk_fma_f32 v[216:217], v[214:215], s[24:25], v[186:187] op_sel_hi:[1,0,0]
	v_max_f32_e32 v220, 0, v208
	v_pk_fma_f32 v[216:217], v[214:215], v[216:217], s[28:29] op_sel_hi:[1,1,0]
	v_max_f32_e32 v221, 0, v209
	v_pk_fma_f32 v[216:217], v[214:215], v[216:217], s[30:31] op_sel_hi:[1,1,0]
	s_nop 0
	v_pk_fma_f32 v[216:217], v[214:215], v[216:217], s[34:35] op_sel_hi:[1,1,0]
	s_nop 0
	v_pk_mul_f32 v[216:217], v[214:215], v[216:217]
	s_nop 0
	v_pk_mul_f32 v[216:217], v[218:219], v[216:217]
	s_nop 0
	v_fma_f32 v208, -|v208|, v216, v220
	v_fma_f32 v209, -|v209|, v217, v221
	v_mul_f32_e32 v208, v212, v208
	v_mul_f32_e32 v209, v213, v209
	v_mov_b64_e32 v[218:219], v[140:141]
	v_cvt_pk_bf16_f32 v220, v206, v207
	v_cvt_pk_bf16_f32 v221, v208, v209
	v_lshl_add_u64 v[126:127], s[68:69], 0, v[184:185]
	global_store_dwordx4 v[126:127], v[218:221], off
	s_and_saveexec_b64 s[22:23], s[76:77]
	s_cbranch_execz .Lmy_p5_11
	s_lshr_b32 s18, s16, 6
	s_add_i32 s18, s18, 2
	s_mul_i32 s18, s18, 0x5800
	s_mov_b32 s19, 0
	v_lshlrev_b64 v[214:215], 2, v[182:183]
	v_lshl_add_u64 v[214:215], s[18:19], 0, v[214:215]
	v_lshl_add_u64 v[214:215], s[92:93], 0, v[214:215]
	global_store_dwordx4 v[214:215], v[4:7], off offset:16
	v_lshl_add_u64 v[216:217], v[214:215], 0, s[52:53]
	global_store_dwordx4 v[216:217], v[0:3], off offset:3088
	s_bfe_u32 s18, s16, 0x60008
	s_cmp_eq_u32 s18, 63
	s_cbranch_scc0 .Lmy_p5_11
	s_lshr_b32 s18, s16, 14
	s_lshl_b32 s18, s18, 1
	s_add_i32 s18, s18, 0
	s_mul_i32 s18, s18, 0x5800
	s_mov_b32 s19, 0
	v_lshlrev_b64 v[214:215], 2, v[182:183]
	v_lshl_add_u64 v[214:215], s[18:19], 0, v[214:215]
	v_lshl_add_u64 v[214:215], s[0:1], 0, v[214:215]
	global_store_dwordx4 v[214:215], v[4:7], off offset:16
	v_lshl_add_u64 v[216:217], v[214:215], 0, s[52:53]
	global_store_dwordx4 v[216:217], v[0:3], off offset:3088
; __device__ __forceinline__ unsigned cvt_pk_bf16(float lo, float hi) { unsigned r; asm volatile("v_cvt_pk_bf16_f32 %0, %1, %2" : "=v"(r) : "v"(lo), "v"(hi)); return r; }
; __device__ __forceinline__ float ror1(float x) { return __builtin_bit_cast(float, __builtin_amdgcn_update_dpp(0, __builtin_bit_cast(int, x), 0x121, 0xf, 0xf, false)); }
; __device__ __forceinline__ f32x2 gelu_pk(f32x2 v) {
;     const f32x2 av = __builtin_elementwise_abs(v), d = av * 0.2316418882f + 1.0f;
;     f32x2 t; t.x = __builtin_amdgcn_rcpf(d.x); t.y = __builtin_amdgcn_rcpf(d.y);
;     f32x2 q = t * 0.5307027145f + (-0.7265760135f); q = q * t + 0.7107068705f; q = q * t + (-0.142248368f); q = q * t + 0.127414796f; q = q * t;
;     const f32x2 s = (v * v) * (-0.72134752044f);
;     f32x2 e; e.x = __builtin_amdgcn_exp2f(s.x); e.y = __builtin_amdgcn_exp2f(s.y);
;     const f32x2 m = v * (q * e), r = v - m;
;     f32x2 o; o.x = v.x < 0.f ? m.x : r.x; o.y = v.y < 0.f ? m.y : r.y; return o;
;     __device__ __forceinline__ void operator()(AccT& acc, const Unit& u, int wr, int wc, int fr, int fq) const {
;     ...
;                     for (int j = 0; j < 4; ++j) {
;                         p1g[j] = ror1(fr == 15 ? hg[j] : cg_[j]); p2g[j] = ror2(fr >= 14 ? hg[j] : cg_[j]);
;                         p1v[j] = ror1(fr == 15 ? hv[j] : cv_[j]); p2v[j] = ror2(fr >= 14 ? hv[j] : cv_[j]);
;                     }
;                     const f32x4 hcg = bg + w0g * p2g + w1g * p1g + w2g * cg_;
;                     const f32x4 hcv = bv + w0v * p2v + w1v * p1v + w2v * cv_;
;                     const f32x2 ga = gelu_pk((f32x2){hcg[0], hcg[1]}), gb2 = gelu_pk((f32x2){hcg[2], hcg[3]});
;                     u32x2 w; w.x = cvt_pk_bf16(ga.x * hcv[0], ga.y * hcv[1]); w.y = cvt_pk_bf16(gb2.x * hcv[2], gb2.y * hcv[3]);
;                     const int t = tstart + rl;
;                     if (n == 0) stash[ai][m] = w;
;                     else if (rl >= 2) *(u32x4*)(U + (size_t)(arow0 + rl) * FF + colg0) = (u32x4){stash[ai][m].x, stash[ai][m].y, w.x, w.y};
;                     if (rl < 2 || rl >= 254) { float* hp = halo + ((size_t)u.pm * 4 + (rl < 2 ? rl : rl - 252)) * FF2; *(f32x4*)(hp + colg) = cg_; *(f32x4*)(hp + colv) = cv_; }
;                     if (t >= SEQ - 2) { float* cp = conv_p + (size_t)(b * 2 + (t - (SEQ - 2))) * FF2; *(f32x4*)(cp + colg) = cg_; *(f32x4*)(cp + colv) = cv_; }
.Lmy_p5_11:
	s_or_b64 exec, exec, s[22:23]
	v_pk_fma_f32 v[206:207], v[102:103], v[12:13], v[98:99]
	v_pk_fma_f32 v[210:211], v[92:93], v[8:9], v[84:85]
	v_pk_fma_f32 v[208:209], v[104:105], v[14:15], v[100:101]
	v_pk_fma_f32 v[212:213], v[94:95], v[10:11], v[86:87]
	v_pk_fma_f32 v[206:207], v[106:107], v[4:5], v[206:207]
	v_pk_fma_f32 v[210:211], v[88:89], v[0:1], v[210:211]
	v_pk_fma_f32 v[208:209], v[108:109], v[6:7], v[208:209]
	v_pk_fma_f32 v[212:213], v[90:91], v[2:3], v[212:213]
	v_pk_fma_f32 v[206:207], v[110:111], v[16:17], v[206:207]
	v_pk_fma_f32 v[210:211], v[80:81], v[20:21], v[210:211]
	v_pk_fma_f32 v[208:209], v[112:113], v[18:19], v[208:209]
	v_pk_fma_f32 v[212:213], v[82:83], v[22:23], v[212:213]
	v_fma_f32 v214, |v206|, s6, 1.0
	v_fma_f32 v215, |v207|, s6, 1.0
	v_pk_mul_f32 v[218:219], v[206:207], v[206:207]
	s_nop 0
	v_pk_mul_f32 v[218:219], v[218:219], s[36:37] op_sel_hi:[1,0]
	v_rcp_f32_e32 v214, v214
	v_rcp_f32_e32 v215, v215
	v_exp_f32_e32 v218, v218
	v_exp_f32_e32 v219, v219
	v_pk_fma_f32 v[216:217], v[214:215], s[24:25], v[186:187] op_sel_hi:[1,0,0]
	v_max_f32_e32 v220, 0, v206
	v_pk_fma_f32 v[216:217], v[214:215], v[216:217], s[28:29] op_sel_hi:[1,1,0]
	v_max_f32_e32 v221, 0, v207
	v_pk_fma_f32 v[216:217], v[214:215], v[216:217], s[30:31] op_sel_hi:[1,1,0]
	s_nop 0
	v_pk_fma_f32 v[216:217], v[214:215], v[216:217], s[34:35] op_sel_hi:[1,1,0]
	s_nop 0
	v_pk_mul_f32 v[216:217], v[214:215], v[216:217]
	s_nop 0
	v_pk_mul_f32 v[216:217], v[218:219], v[216:217]
	s_nop 0
	v_fma_f32 v206, -|v206|, v216, v220
	v_fma_f32 v207, -|v207|, v217, v221
	v_mul_f32_e32 v206, v210, v206
	v_mul_f32_e32 v207, v211, v207
	v_fma_f32 v214, |v208|, s6, 1.0
	v_fma_f32 v215, |v209|, s6, 1.0
	v_pk_mul_f32 v[218:219], v[208:209], v[208:209]
	s_nop 0
	v_pk_mul_f32 v[218:219], v[218:219], s[36:37] op_sel_hi:[1,0]
	v_rcp_f32_e32 v214, v214
	v_rcp_f32_e32 v215, v215
	v_exp_f32_e32 v218, v218
	v_exp_f32_e32 v219, v219
	v_pk_fma_f32 v[216:217], v[214:215], s[24:25], v[186:187] op_sel_hi:[1,0,0]
	v_max_f32_e32 v220, 0, v208
	v_pk_fma_f32 v[216:217], v[214:215], v[216:217], s[28:29] op_sel_hi:[1,1,0]
	v_max_f32_e32 v221, 0, v209
	v_pk_fma_f32 v[216:217], v[214:215], v[216:217], s[30:31] op_sel_hi:[1,1,0]
	s_nop 0
	v_pk_fma_f32 v[216:217], v[214:215], v[216:217], s[34:35] op_sel_hi:[1,1,0]
	s_nop 0
	v_pk_mul_f32 v[216:217], v[214:215], v[216:217]
	s_nop 0
	v_pk_mul_f32 v[216:217], v[218:219], v[216:217]
	s_nop 0
	v_fma_f32 v208, -|v208|, v216, v220
	v_fma_f32 v209, -|v209|, v217, v221
	v_mul_f32_e32 v208, v212, v208
	v_mul_f32_e32 v209, v213, v209
	v_mov_b64_e32 v[218:219], v[152:153]
	v_cvt_pk_bf16_f32 v220, v206, v207
	v_cvt_pk_bf16_f32 v221, v208, v209
	v_lshl_add_u64 v[126:127], s[70:71], 0, v[184:185]
	global_store_dwordx4 v[126:127], v[218:221], off
	s_and_saveexec_b64 s[22:23], s[76:77]
	s_cbranch_execz .Lmy_p5_12
	s_lshr_b32 s18, s16, 6
	s_add_i32 s18, s18, 3
	s_mul_i32 s18, s18, 0x5800
	s_mov_b32 s19, 0
	v_lshlrev_b64 v[214:215], 2, v[182:183]
	v_lshl_add_u64 v[214:215], s[18:19], 0, v[214:215]
	v_lshl_add_u64 v[214:215], s[92:93], 0, v[214:215]
	global_store_dwordx4 v[214:215], v[16:19], off offset:16
	v_lshl_add_u64 v[216:217], v[214:215], 0, s[52:53]
	global_store_dwordx4 v[216:217], v[20:23], off offset:3088
	s_bfe_u32 s18, s16, 0x60008
	s_cmp_eq_u32 s18, 63
	s_cbranch_scc0 .Lmy_p5_12
	s_lshr_b32 s18, s16, 14
	s_lshl_b32 s18, s18, 1
	s_add_i32 s18, s18, 1
	s_mul_i32 s18, s18, 0x5800
	s_mov_b32 s19, 0
	v_lshlrev_b64 v[214:215], 2, v[182:183]
	v_lshl_add_u64 v[214:215], s[18:19], 0, v[214:215]
	v_lshl_add_u64 v[214:215], s[0:1], 0, v[214:215]
	global_store_dwordx4 v[214:215], v[16:19], off offset:16
	v_lshl_add_u64 v[216:217], v[214:215], 0, s[52:53]
	global_store_dwordx4 v[216:217], v[20:23], off offset:3088
